# baseline (speedup 1.0000x reference)
.Lglds2_2829:
	ds_read_b128 v[152:155], v112 offset:16384
	ds_read_b128 v[156:159], v112 offset:18432
	ds_read_b128 v[160:163], v110
	ds_read_b128 v[164:167], v110 offset:2048
	ds_read_b128 v[168:171], v112 offset:20480
	ds_read_b128 v[172:175], v113 offset:16384
	ds_read_b128 v[208:211], v110 offset:4096
	ds_read_b128 v[212:215], v111
	ds_read_b128 v[216:219], v116 offset:16384
	ds_read_b128 v[220:223], v116 offset:18432
	ds_read_b128 v[224:227], v114
	ds_read_b128 v[228:231], v114 offset:2048
	ds_read_b128 v[232:235], v116 offset:20480
	ds_read_b128 v[236:239], v117 offset:16384
	ds_read_b128 v[240:243], v114 offset:4096
	ds_read_b128 v[244:247], v115
	s_setprio 1
	s_waitcnt lgkmcnt(13)
	v_mfma_f32_16x16x32_bf16 v[94:97], v[152:155], v[160:163], v[94:97]
	v_mfma_f32_16x16x32_bf16 v[90:93], v[156:159], v[160:163], v[90:93]
	s_waitcnt lgkmcnt(11)
	v_mfma_f32_16x16x32_bf16 v[86:89], v[168:171], v[160:163], v[86:89]
	s_waitcnt lgkmcnt(10)
	v_mfma_f32_16x16x32_bf16 v[82:85], v[172:175], v[160:163], v[82:85]
	v_mfma_f32_16x16x32_bf16 v[78:81], v[152:155], v[164:167], v[78:81]
	v_mfma_f32_16x16x32_bf16 v[62:65], v[156:159], v[164:167], v[62:65]
	v_mfma_f32_16x16x32_bf16 v[46:49], v[168:171], v[164:167], v[46:49]
	v_mfma_f32_16x16x32_bf16 v[26:29], v[172:175], v[164:167], v[26:29]
	s_waitcnt lgkmcnt(9)
	v_mfma_f32_16x16x32_bf16 v[38:41], v[152:155], v[208:211], v[38:41]
	v_mfma_f32_16x16x32_bf16 v[30:33], v[156:159], v[208:211], v[30:33]
	v_mfma_f32_16x16x32_bf16 v[22:25], v[168:171], v[208:211], v[22:25]
	v_mfma_f32_16x16x32_bf16 v[18:21], v[172:175], v[208:211], v[18:21]
	s_waitcnt lgkmcnt(8)
	v_mfma_f32_16x16x32_bf16 v[14:17], v[152:155], v[212:215], v[14:17]
	v_mfma_f32_16x16x32_bf16 v[10:13], v[156:159], v[212:215], v[10:13]
	v_mfma_f32_16x16x32_bf16 v[6:9], v[168:171], v[212:215], v[6:9]
	v_mfma_f32_16x16x32_bf16 v[2:5], v[172:175], v[212:215], v[2:5]
	s_setprio 0
	s_waitcnt lgkmcnt(0)
	s_barrier
	s_add_i32 s0, s5, 0x80
	s_min_u32 s0, s0, 0x3c0
	s_lshl_b32 s0, s0, 1
	s_setprio 1
	v_mfma_f32_16x16x32_bf16 v[94:97], v[216:219], v[224:227], v[94:97]
	s_add_u32 m0, s6, 0x0
	v_lshl_add_u64 v[204:205], v[188:189], 0, s[0:1]
	global_load_lds_dwordx4 v[204:205], off
	v_mfma_f32_16x16x32_bf16 v[90:93], v[220:223], v[224:227], v[90:93]
	v_mfma_f32_16x16x32_bf16 v[86:89], v[232:235], v[224:227], v[86:89]
	s_add_u32 m0, s6, 0x1000
	v_lshl_add_u64 v[206:207], v[190:191], 0, s[0:1]
	global_load_lds_dwordx4 v[206:207], off
	v_mfma_f32_16x16x32_bf16 v[82:85], v[236:239], v[224:227], v[82:85]
	v_mfma_f32_16x16x32_bf16 v[78:81], v[216:219], v[228:231], v[78:81]
	s_add_u32 m0, s6, 0x2000
	v_lshl_add_u64 v[204:205], v[192:193], 0, s[0:1]
	global_load_lds_dwordx4 v[204:205], off
	v_mfma_f32_16x16x32_bf16 v[62:65], v[220:223], v[228:231], v[62:65]
	v_mfma_f32_16x16x32_bf16 v[46:49], v[232:235], v[228:231], v[46:49]
	s_add_u32 m0, s6, 0x3000
	v_lshl_add_u64 v[206:207], v[194:195], 0, s[0:1]
	global_load_lds_dwordx4 v[206:207], off
	v_mfma_f32_16x16x32_bf16 v[26:29], v[236:239], v[228:231], v[26:29]
	v_mfma_f32_16x16x32_bf16 v[38:41], v[216:219], v[240:243], v[38:41]
	s_add_u32 m0, s6, 0x4000
	v_lshl_add_u64 v[204:205], v[196:197], 0, s[0:1]
	global_load_lds_dwordx4 v[204:205], off
	v_mfma_f32_16x16x32_bf16 v[30:33], v[220:223], v[240:243], v[30:33]
	v_mfma_f32_16x16x32_bf16 v[22:25], v[232:235], v[240:243], v[22:25]
	s_add_u32 m0, s6, 0x5000
	v_lshl_add_u64 v[206:207], v[198:199], 0, s[0:1]
	global_load_lds_dwordx4 v[206:207], off
	v_mfma_f32_16x16x32_bf16 v[18:21], v[236:239], v[240:243], v[18:21]
	v_mfma_f32_16x16x32_bf16 v[14:17], v[216:219], v[244:247], v[14:17]
	s_add_u32 m0, s6, 0x6000
	v_lshl_add_u64 v[204:205], v[200:201], 0, s[0:1]
	global_load_lds_dwordx4 v[204:205], off
	v_mfma_f32_16x16x32_bf16 v[10:13], v[220:223], v[244:247], v[10:13]
	v_mfma_f32_16x16x32_bf16 v[6:9], v[232:235], v[244:247], v[6:9]
	s_add_u32 m0, s6, 0x7000
	v_lshl_add_u64 v[206:207], v[202:203], 0, s[0:1]
	global_load_lds_dwordx4 v[206:207], off
	v_mfma_f32_16x16x32_bf16 v[2:5], v[236:239], v[244:247], v[2:5]
	s_setprio 0
	s_waitcnt vmcnt(8)
	s_barrier
	ds_read_b128 v[152:155], v112 offset:49152
	ds_read_b128 v[156:159], v112 offset:51200
	ds_read_b128 v[160:163], v110 offset:32768
	ds_read_b128 v[164:167], v110 offset:34816
	ds_read_b128 v[168:171], v112 offset:53248
	ds_read_b128 v[172:175], v113 offset:49152
	ds_read_b128 v[208:211], v110 offset:36864
	ds_read_b128 v[212:215], v111 offset:32768
	ds_read_b128 v[216:219], v116 offset:49152
	ds_read_b128 v[220:223], v116 offset:51200
	ds_read_b128 v[224:227], v114 offset:32768
	ds_read_b128 v[228:231], v114 offset:34816
	ds_read_b128 v[232:235], v116 offset:53248
	ds_read_b128 v[236:239], v117 offset:49152
	ds_read_b128 v[240:243], v114 offset:36864
	ds_read_b128 v[244:247], v115 offset:32768
	s_setprio 1
	s_waitcnt lgkmcnt(13)
	v_mfma_f32_16x16x32_bf16 v[94:97], v[152:155], v[160:163], v[94:97]
	v_mfma_f32_16x16x32_bf16 v[90:93], v[156:159], v[160:163], v[90:93]
	s_waitcnt lgkmcnt(11)
	v_mfma_f32_16x16x32_bf16 v[86:89], v[168:171], v[160:163], v[86:89]
	s_waitcnt lgkmcnt(10)
	v_mfma_f32_16x16x32_bf16 v[82:85], v[172:175], v[160:163], v[82:85]
	v_mfma_f32_16x16x32_bf16 v[78:81], v[152:155], v[164:167], v[78:81]
	v_mfma_f32_16x16x32_bf16 v[62:65], v[156:159], v[164:167], v[62:65]
	v_mfma_f32_16x16x32_bf16 v[46:49], v[168:171], v[164:167], v[46:49]
	v_mfma_f32_16x16x32_bf16 v[26:29], v[172:175], v[164:167], v[26:29]
	s_waitcnt lgkmcnt(9)
	v_mfma_f32_16x16x32_bf16 v[38:41], v[152:155], v[208:211], v[38:41]
	v_mfma_f32_16x16x32_bf16 v[30:33], v[156:159], v[208:211], v[30:33]
	v_mfma_f32_16x16x32_bf16 v[22:25], v[168:171], v[208:211], v[22:25]
	v_mfma_f32_16x16x32_bf16 v[18:21], v[172:175], v[208:211], v[18:21]
	s_waitcnt lgkmcnt(8)
	v_mfma_f32_16x16x32_bf16 v[14:17], v[152:155], v[212:215], v[14:17]
	v_mfma_f32_16x16x32_bf16 v[10:13], v[156:159], v[212:215], v[10:13]
	v_mfma_f32_16x16x32_bf16 v[6:9], v[168:171], v[212:215], v[6:9]
	v_mfma_f32_16x16x32_bf16 v[2:5], v[172:175], v[212:215], v[2:5]
	s_setprio 0
	s_waitcnt lgkmcnt(0)
	s_barrier
	s_add_i32 s0, s5, 0xc0
	s_min_u32 s0, s0, 0x3c0
	s_lshl_b32 s0, s0, 1
	s_setprio 1
	v_mfma_f32_16x16x32_bf16 v[94:97], v[216:219], v[224:227], v[94:97]
	s_add_u32 m0, s6, 0x8000
	v_lshl_add_u64 v[204:205], v[188:189], 0, s[0:1]
	global_load_lds_dwordx4 v[204:205], off
	v_mfma_f32_16x16x32_bf16 v[90:93], v[220:223], v[224:227], v[90:93]
	v_mfma_f32_16x16x32_bf16 v[86:89], v[232:235], v[224:227], v[86:89]
	s_add_u32 m0, s6, 0x9000
	v_lshl_add_u64 v[206:207], v[190:191], 0, s[0:1]
	global_load_lds_dwordx4 v[206:207], off
	v_mfma_f32_16x16x32_bf16 v[82:85], v[236:239], v[224:227], v[82:85]
	v_mfma_f32_16x16x32_bf16 v[78:81], v[216:219], v[228:231], v[78:81]
	s_add_u32 m0, s6, 0xa000
	v_lshl_add_u64 v[204:205], v[192:193], 0, s[0:1]
	global_load_lds_dwordx4 v[204:205], off
	v_mfma_f32_16x16x32_bf16 v[62:65], v[220:223], v[228:231], v[62:65]
	v_mfma_f32_16x16x32_bf16 v[46:49], v[232:235], v[228:231], v[46:49]
	s_add_u32 m0, s6, 0xb000
	v_lshl_add_u64 v[206:207], v[194:195], 0, s[0:1]
	global_load_lds_dwordx4 v[206:207], off
	v_mfma_f32_16x16x32_bf16 v[26:29], v[236:239], v[228:231], v[26:29]
	v_mfma_f32_16x16x32_bf16 v[38:41], v[216:219], v[240:243], v[38:41]
	s_add_u32 m0, s6, 0xc000
	v_lshl_add_u64 v[204:205], v[196:197], 0, s[0:1]
	global_load_lds_dwordx4 v[204:205], off
	v_mfma_f32_16x16x32_bf16 v[30:33], v[220:223], v[240:243], v[30:33]
	v_mfma_f32_16x16x32_bf16 v[22:25], v[232:235], v[240:243], v[22:25]
	s_add_u32 m0, s6, 0xd000
	v_lshl_add_u64 v[206:207], v[198:199], 0, s[0:1]
	global_load_lds_dwordx4 v[206:207], off
	v_mfma_f32_16x16x32_bf16 v[18:21], v[236:239], v[240:243], v[18:21]
	v_mfma_f32_16x16x32_bf16 v[14:17], v[216:219], v[244:247], v[14:17]
	s_add_u32 m0, s6, 0xe000
	v_lshl_add_u64 v[204:205], v[200:201], 0, s[0:1]
	global_load_lds_dwordx4 v[204:205], off
	v_mfma_f32_16x16x32_bf16 v[10:13], v[220:223], v[244:247], v[10:13]
	v_mfma_f32_16x16x32_bf16 v[6:9], v[232:235], v[244:247], v[6:9]
	s_add_u32 m0, s6, 0xf000
	v_lshl_add_u64 v[206:207], v[202:203], 0, s[0:1]
	global_load_lds_dwordx4 v[206:207], off
	v_mfma_f32_16x16x32_bf16 v[2:5], v[236:239], v[244:247], v[2:5]
	s_setprio 0
	s_waitcnt vmcnt(8)
	s_barrier
	s_add_i32 s5, s5, 0x80
	s_add_i32 s4, s4, 2
	s_cmp_gt_u32 s4, 13
	s_cbranch_scc0 .Lglds2_2829
	s_waitcnt vmcnt(0)
	v_readlane_b32 s36, v254, 40
	s_waitcnt vmcnt(7)
	v_or_b32_e32 v35, s2, v118
	v_readlane_b32 s48, v254, 52
	v_readlane_b32 s49, v254, 53
	v_or_b32_e32 v34, s3, v119
	s_waitcnt vmcnt(6)
	v_add_u32_e32 v42, v35, v120
	v_mov_b64_e32 v[36:37], s[48:49]
	v_mad_i64_i32 v[36:37], s[2:3], v42, s18, v[36:37]
	v_cmp_gt_i32_e32 vcc, s19, v34
	v_ashrrev_i32_e32 v35, 31, v34
	v_readlane_b32 s37, v254, 41
	v_readlane_b32 s38, v254, 42
	v_readlane_b32 s39, v254, 43
	v_readlane_b32 s40, v254, 44
	v_readlane_b32 s41, v254, 45
	v_readlane_b32 s42, v254, 46
	v_readlane_b32 s43, v254, 47
	v_readlane_b32 s44, v254, 48
	v_readlane_b32 s45, v254, 49
	v_readlane_b32 s46, v254, 50
	v_readlane_b32 s47, v254, 51
	v_readlane_b32 s50, v254, 54
	v_readlane_b32 s51, v254, 55
	s_and_saveexec_b64 s[2:3], vcc
	s_cbranch_execnz .LBB0_205
	s_or_b64 exec, exec, s[2:3]
	v_cmp_gt_i32_e64 s[4:5], s20, v34
	s_and_saveexec_b64 s[2:3], s[4:5]
	s_cbranch_execnz .LBB0_206

.Lglds2_3547:
	ds_read_b128 v[152:155], v112 offset:16384
	ds_read_b128 v[156:159], v112 offset:18432
	ds_read_b128 v[160:163], v110
	ds_read_b128 v[164:167], v110 offset:2048
	ds_read_b128 v[168:171], v112 offset:20480
	ds_read_b128 v[172:175], v113 offset:16384
	ds_read_b128 v[208:211], v110 offset:4096
	ds_read_b128 v[212:215], v111
	ds_read_b128 v[216:219], v116 offset:16384
	ds_read_b128 v[220:223], v116 offset:18432
	ds_read_b128 v[224:227], v114
	ds_read_b128 v[228:231], v114 offset:2048
	ds_read_b128 v[232:235], v116 offset:20480
	ds_read_b128 v[236:239], v117 offset:16384
	ds_read_b128 v[240:243], v114 offset:4096
	ds_read_b128 v[244:247], v115
	s_setprio 1
	s_waitcnt lgkmcnt(13)
	v_mfma_f32_16x16x32_bf16 v[94:97], v[152:155], v[160:163], v[94:97]
	v_mfma_f32_16x16x32_bf16 v[90:93], v[156:159], v[160:163], v[90:93]
	s_waitcnt lgkmcnt(11)
	v_mfma_f32_16x16x32_bf16 v[86:89], v[168:171], v[160:163], v[86:89]
	s_waitcnt lgkmcnt(10)
	v_mfma_f32_16x16x32_bf16 v[82:85], v[172:175], v[160:163], v[82:85]
	v_mfma_f32_16x16x32_bf16 v[78:81], v[152:155], v[164:167], v[78:81]
	v_mfma_f32_16x16x32_bf16 v[54:57], v[156:159], v[164:167], v[54:57]
	v_mfma_f32_16x16x32_bf16 v[38:41], v[168:171], v[164:167], v[38:41]
	v_mfma_f32_16x16x32_bf16 v[34:37], v[172:175], v[164:167], v[34:37]
	s_waitcnt lgkmcnt(9)
	v_mfma_f32_16x16x32_bf16 v[74:77], v[152:155], v[208:211], v[74:77]
	v_mfma_f32_16x16x32_bf16 v[70:73], v[156:159], v[208:211], v[70:73]
	v_mfma_f32_16x16x32_bf16 v[66:69], v[168:171], v[208:211], v[66:69]
	v_mfma_f32_16x16x32_bf16 v[62:65], v[172:175], v[208:211], v[62:65]
	s_waitcnt lgkmcnt(8)
	v_mfma_f32_16x16x32_bf16 v[58:61], v[152:155], v[212:215], v[58:61]
	v_mfma_f32_16x16x32_bf16 v[50:53], v[156:159], v[212:215], v[50:53]
	v_mfma_f32_16x16x32_bf16 v[46:49], v[168:171], v[212:215], v[46:49]
	v_mfma_f32_16x16x32_bf16 v[42:45], v[172:175], v[212:215], v[42:45]
	s_setprio 0
	s_waitcnt lgkmcnt(0)
	s_barrier
	s_add_i32 s0, s19, 0x80
	s_min_u32 s0, s0, 0x3c0
	s_lshl_b32 s0, s0, 1
	s_setprio 1
	v_mfma_f32_16x16x32_bf16 v[94:97], v[216:219], v[224:227], v[94:97]
	s_add_u32 m0, s20, 0x0
	v_lshl_add_u64 v[204:205], v[188:189], 0, s[0:1]
	global_load_lds_dwordx4 v[204:205], off
	v_mfma_f32_16x16x32_bf16 v[90:93], v[220:223], v[224:227], v[90:93]
	v_mfma_f32_16x16x32_bf16 v[86:89], v[232:235], v[224:227], v[86:89]
	s_add_u32 m0, s20, 0x1000
	v_lshl_add_u64 v[206:207], v[190:191], 0, s[0:1]
	global_load_lds_dwordx4 v[206:207], off
	v_mfma_f32_16x16x32_bf16 v[82:85], v[236:239], v[224:227], v[82:85]
	v_mfma_f32_16x16x32_bf16 v[78:81], v[216:219], v[228:231], v[78:81]
	s_add_u32 m0, s20, 0x2000
	v_lshl_add_u64 v[204:205], v[192:193], 0, s[0:1]
	global_load_lds_dwordx4 v[204:205], off
	v_mfma_f32_16x16x32_bf16 v[54:57], v[220:223], v[228:231], v[54:57]
	v_mfma_f32_16x16x32_bf16 v[38:41], v[232:235], v[228:231], v[38:41]
	s_add_u32 m0, s20, 0x3000
	v_lshl_add_u64 v[206:207], v[194:195], 0, s[0:1]
	global_load_lds_dwordx4 v[206:207], off
	v_mfma_f32_16x16x32_bf16 v[34:37], v[236:239], v[228:231], v[34:37]
	v_mfma_f32_16x16x32_bf16 v[74:77], v[216:219], v[240:243], v[74:77]
	s_add_u32 m0, s20, 0x4000
	v_lshl_add_u64 v[204:205], v[196:197], 0, s[0:1]
	global_load_lds_dwordx4 v[204:205], off
	v_mfma_f32_16x16x32_bf16 v[70:73], v[220:223], v[240:243], v[70:73]
	v_mfma_f32_16x16x32_bf16 v[66:69], v[232:235], v[240:243], v[66:69]
	s_add_u32 m0, s20, 0x5000
	v_lshl_add_u64 v[206:207], v[198:199], 0, s[0:1]
	global_load_lds_dwordx4 v[206:207], off
	v_mfma_f32_16x16x32_bf16 v[62:65], v[236:239], v[240:243], v[62:65]
	v_mfma_f32_16x16x32_bf16 v[58:61], v[216:219], v[244:247], v[58:61]
	s_add_u32 m0, s20, 0x6000
	v_lshl_add_u64 v[204:205], v[200:201], 0, s[0:1]
	global_load_lds_dwordx4 v[204:205], off
	v_mfma_f32_16x16x32_bf16 v[50:53], v[220:223], v[244:247], v[50:53]
	v_mfma_f32_16x16x32_bf16 v[46:49], v[232:235], v[244:247], v[46:49]
	s_add_u32 m0, s20, 0x7000
	v_lshl_add_u64 v[206:207], v[202:203], 0, s[0:1]
	global_load_lds_dwordx4 v[206:207], off
	v_mfma_f32_16x16x32_bf16 v[42:45], v[236:239], v[244:247], v[42:45]
	s_setprio 0
	s_waitcnt vmcnt(8)
	s_barrier
	ds_read_b128 v[152:155], v112 offset:49152
	ds_read_b128 v[156:159], v112 offset:51200
	ds_read_b128 v[160:163], v110 offset:32768
	ds_read_b128 v[164:167], v110 offset:34816
	ds_read_b128 v[168:171], v112 offset:53248
	ds_read_b128 v[172:175], v113 offset:49152
	ds_read_b128 v[208:211], v110 offset:36864
	ds_read_b128 v[212:215], v111 offset:32768
	ds_read_b128 v[216:219], v116 offset:49152
	ds_read_b128 v[220:223], v116 offset:51200
	ds_read_b128 v[224:227], v114 offset:32768
	ds_read_b128 v[228:231], v114 offset:34816
	ds_read_b128 v[232:235], v116 offset:53248
	ds_read_b128 v[236:239], v117 offset:49152
	ds_read_b128 v[240:243], v114 offset:36864
	ds_read_b128 v[244:247], v115 offset:32768
	s_setprio 1
	s_waitcnt lgkmcnt(13)
	v_mfma_f32_16x16x32_bf16 v[94:97], v[152:155], v[160:163], v[94:97]
	v_mfma_f32_16x16x32_bf16 v[90:93], v[156:159], v[160:163], v[90:93]
	s_waitcnt lgkmcnt(11)
	v_mfma_f32_16x16x32_bf16 v[86:89], v[168:171], v[160:163], v[86:89]
	s_waitcnt lgkmcnt(10)
	v_mfma_f32_16x16x32_bf16 v[82:85], v[172:175], v[160:163], v[82:85]
	v_mfma_f32_16x16x32_bf16 v[78:81], v[152:155], v[164:167], v[78:81]
	v_mfma_f32_16x16x32_bf16 v[54:57], v[156:159], v[164:167], v[54:57]
	v_mfma_f32_16x16x32_bf16 v[38:41], v[168:171], v[164:167], v[38:41]
	v_mfma_f32_16x16x32_bf16 v[34:37], v[172:175], v[164:167], v[34:37]
	s_waitcnt lgkmcnt(9)
	v_mfma_f32_16x16x32_bf16 v[74:77], v[152:155], v[208:211], v[74:77]
	v_mfma_f32_16x16x32_bf16 v[70:73], v[156:159], v[208:211], v[70:73]
	v_mfma_f32_16x16x32_bf16 v[66:69], v[168:171], v[208:211], v[66:69]
	v_mfma_f32_16x16x32_bf16 v[62:65], v[172:175], v[208:211], v[62:65]
	s_waitcnt lgkmcnt(8)
	v_mfma_f32_16x16x32_bf16 v[58:61], v[152:155], v[212:215], v[58:61]
	v_mfma_f32_16x16x32_bf16 v[50:53], v[156:159], v[212:215], v[50:53]
	v_mfma_f32_16x16x32_bf16 v[46:49], v[168:171], v[212:215], v[46:49]
	v_mfma_f32_16x16x32_bf16 v[42:45], v[172:175], v[212:215], v[42:45]
	s_setprio 0
	s_waitcnt lgkmcnt(0)
	s_barrier
	s_add_i32 s0, s19, 0xc0
	s_min_u32 s0, s0, 0x3c0
	s_lshl_b32 s0, s0, 1
	s_setprio 1
	v_mfma_f32_16x16x32_bf16 v[94:97], v[216:219], v[224:227], v[94:97]
	s_add_u32 m0, s20, 0x8000
	v_lshl_add_u64 v[204:205], v[188:189], 0, s[0:1]
	global_load_lds_dwordx4 v[204:205], off
	v_mfma_f32_16x16x32_bf16 v[90:93], v[220:223], v[224:227], v[90:93]
	v_mfma_f32_16x16x32_bf16 v[86:89], v[232:235], v[224:227], v[86:89]
	s_add_u32 m0, s20, 0x9000
	v_lshl_add_u64 v[206:207], v[190:191], 0, s[0:1]
	global_load_lds_dwordx4 v[206:207], off
	v_mfma_f32_16x16x32_bf16 v[82:85], v[236:239], v[224:227], v[82:85]
	v_mfma_f32_16x16x32_bf16 v[78:81], v[216:219], v[228:231], v[78:81]
	s_add_u32 m0, s20, 0xa000
	v_lshl_add_u64 v[204:205], v[192:193], 0, s[0:1]
	global_load_lds_dwordx4 v[204:205], off
	v_mfma_f32_16x16x32_bf16 v[54:57], v[220:223], v[228:231], v[54:57]
	v_mfma_f32_16x16x32_bf16 v[38:41], v[232:235], v[228:231], v[38:41]
	s_add_u32 m0, s20, 0xb000
	v_lshl_add_u64 v[206:207], v[194:195], 0, s[0:1]
	global_load_lds_dwordx4 v[206:207], off
	v_mfma_f32_16x16x32_bf16 v[34:37], v[236:239], v[228:231], v[34:37]
	v_mfma_f32_16x16x32_bf16 v[74:77], v[216:219], v[240:243], v[74:77]
	s_add_u32 m0, s20, 0xc000
	v_lshl_add_u64 v[204:205], v[196:197], 0, s[0:1]
	global_load_lds_dwordx4 v[204:205], off
	v_mfma_f32_16x16x32_bf16 v[70:73], v[220:223], v[240:243], v[70:73]
	v_mfma_f32_16x16x32_bf16 v[66:69], v[232:235], v[240:243], v[66:69]
	s_add_u32 m0, s20, 0xd000
	v_lshl_add_u64 v[206:207], v[198:199], 0, s[0:1]
	global_load_lds_dwordx4 v[206:207], off
	v_mfma_f32_16x16x32_bf16 v[62:65], v[236:239], v[240:243], v[62:65]
	v_mfma_f32_16x16x32_bf16 v[58:61], v[216:219], v[244:247], v[58:61]
	s_add_u32 m0, s20, 0xe000
	v_lshl_add_u64 v[204:205], v[200:201], 0, s[0:1]
	global_load_lds_dwordx4 v[204:205], off
	v_mfma_f32_16x16x32_bf16 v[50:53], v[220:223], v[244:247], v[50:53]
	v_mfma_f32_16x16x32_bf16 v[46:49], v[232:235], v[244:247], v[46:49]
	s_add_u32 m0, s20, 0xf000
	v_lshl_add_u64 v[206:207], v[202:203], 0, s[0:1]
	global_load_lds_dwordx4 v[206:207], off
	v_mfma_f32_16x16x32_bf16 v[42:45], v[236:239], v[244:247], v[42:45]
	s_setprio 0
	s_waitcnt vmcnt(8)
	s_barrier
	s_add_i32 s19, s19, 0x80
	s_add_i32 s18, s18, 2
	s_cmp_lt_u32 s18, 14
	s_cbranch_scc1 .Lglds2_3547
	s_waitcnt vmcnt(0)
	v_readlane_b32 s36, v254, 40
	s_lshl_b64 s[12:13], s[12:13], 21
	v_readlane_b32 s50, v254, 54
	v_readlane_b32 s51, v254, 55
	s_add_u32 s12, s50, s12
	s_addc_u32 s13, s51, s13
	s_waitcnt vmcnt(7)
	v_or_b32_e32 v4, s17, v119
	v_add_lshl_u32 v98, v118, s16, 10
	v_lshl_add_u64 v[2:3], s[12:13], 0, v[98:99]
	v_lshlrev_b32_e32 v98, 1, v4
	v_lshl_add_u64 v[4:5], v[2:3], 0, v[98:99]
	s_waitcnt vmcnt(6)
	v_cvt_pk_bf16_f32 v6, v94, v95
	v_cvt_pk_bf16_f32 v7, v96, v97
	global_store_dwordx2 v[4:5], v[6:7], off
	v_cvt_pk_bf16_f32 v6, v90, v91
	v_cvt_pk_bf16_f32 v7, v92, v93
	global_store_dwordx2 v[4:5], v[6:7], off offset:32
	v_cvt_pk_bf16_f32 v6, v86, v87
	v_cvt_pk_bf16_f32 v7, v88, v89
	global_store_dwordx2 v[4:5], v[6:7], off offset:64
	v_cvt_pk_bf16_f32 v6, v82, v83
	v_cvt_pk_bf16_f32 v7, v84, v85
	global_store_dwordx2 v[4:5], v[6:7], off offset:96
	v_lshl_add_u64 v[4:5], v[2:3], 0, s[4:5]
	v_lshl_add_u64 v[6:7], v[4:5], 0, v[98:99]
	v_cvt_pk_bf16_f32 v8, v78, v79
	v_cvt_pk_bf16_f32 v9, v80, v81
	global_store_dwordx2 v[6:7], v[8:9], off
	v_or_b32_e32 v6, 32, v98
	v_mov_b32_e32 v7, v99
	v_lshl_add_u64 v[8:9], v[4:5], 0, v[6:7]
	s_waitcnt vmcnt(10)
	v_cvt_pk_bf16_f32 v10, v54, v55
	v_cvt_pk_bf16_f32 v11, v56, v57
	global_store_dwordx2 v[8:9], v[10:11], off
	v_or_b32_e32 v8, 64, v98
	v_mov_b32_e32 v9, v99
	v_lshl_add_u64 v[10:11], v[4:5], 0, v[8:9]
	v_cvt_pk_bf16_f32 v12, v38, v39
	v_cvt_pk_bf16_f32 v13, v40, v41
	global_store_dwordx2 v[10:11], v[12:13], off
	v_or_b32_e32 v10, 0x60, v98
	v_mov_b32_e32 v11, v99
	v_lshl_add_u64 v[4:5], v[4:5], 0, v[10:11]
	v_cvt_pk_bf16_f32 v12, v34, v35
	v_cvt_pk_bf16_f32 v13, v36, v37
	global_store_dwordx2 v[4:5], v[12:13], off
	v_lshl_add_u64 v[4:5], v[2:3], 0, s[6:7]
	v_lshl_add_u64 v[12:13], v[4:5], 0, v[98:99]
	s_waitcnt vmcnt(11)
	v_cvt_pk_bf16_f32 v14, v74, v75
	v_cvt_pk_bf16_f32 v15, v76, v77
	global_store_dwordx2 v[12:13], v[14:15], off
	v_lshl_add_u64 v[12:13], v[4:5], 0, v[6:7]
	v_cvt_pk_bf16_f32 v14, v70, v71
	v_cvt_pk_bf16_f32 v15, v72, v73
	global_store_dwordx2 v[12:13], v[14:15], off
	v_lshl_add_u64 v[12:13], v[4:5], 0, v[8:9]
	v_cvt_pk_bf16_f32 v14, v66, v67
	v_cvt_pk_bf16_f32 v15, v68, v69
	global_store_dwordx2 v[12:13], v[14:15], off
	v_lshl_add_u64 v[4:5], v[4:5], 0, v[10:11]
	v_cvt_pk_bf16_f32 v12, v62, v63
	v_cvt_pk_bf16_f32 v13, v64, v65
	v_lshl_add_u64 v[2:3], v[2:3], 0, s[8:9]
	global_store_dwordx2 v[4:5], v[12:13], off
	v_lshl_add_u64 v[4:5], v[2:3], 0, v[98:99]
	v_cvt_pk_bf16_f32 v12, v58, v59
	v_cvt_pk_bf16_f32 v13, v60, v61
	global_store_dwordx2 v[4:5], v[12:13], off
	v_lshl_add_u64 v[4:5], v[2:3], 0, v[6:7]
	v_cvt_pk_bf16_f32 v6, v50, v51
	v_cvt_pk_bf16_f32 v7, v52, v53
	v_readlane_b32 s12, v254, 0
	global_store_dwordx2 v[4:5], v[6:7], off
	v_lshl_add_u64 v[4:5], v[2:3], 0, v[8:9]
	v_cvt_pk_bf16_f32 v6, v46, v47
	v_cvt_pk_bf16_f32 v7, v48, v49
	s_add_i32 s2, s2, s12
	v_readlane_b32 s37, v254, 41
	global_store_dwordx2 v[4:5], v[6:7], off
	v_lshl_add_u64 v[2:3], v[2:3], 0, v[10:11]
	v_cvt_pk_bf16_f32 v4, v42, v43
	v_cvt_pk_bf16_f32 v5, v44, v45
	s_cmpk_lt_i32 s2, 0x80
	v_readlane_b32 s38, v254, 42
	v_readlane_b32 s39, v254, 43
	v_readlane_b32 s40, v254, 44
	v_readlane_b32 s41, v254, 45
	v_readlane_b32 s42, v254, 46
	v_readlane_b32 s43, v254, 47
	v_readlane_b32 s44, v254, 48
	v_readlane_b32 s45, v254, 49
	v_readlane_b32 s46, v254, 50
	v_readlane_b32 s47, v254, 51
	v_readlane_b32 s48, v254, 52
	v_readlane_b32 s49, v254, 53
	v_readlane_b32 s13, v254, 1
	global_store_dwordx2 v[2:3], v[4:5], off
	s_cbranch_scc1 .LBB0_220

.Lglds2_12468:
	ds_read_b128 v[152:155], v112 offset:16384
	ds_read_b128 v[156:159], v112 offset:18432
	ds_read_b128 v[160:163], v110
	ds_read_b128 v[164:167], v110 offset:2048
	ds_read_b128 v[168:171], v112 offset:20480
	ds_read_b128 v[172:175], v113 offset:16384
	ds_read_b128 v[204:207], v110 offset:4096
	ds_read_b128 v[208:211], v111
	ds_read_b128 v[212:215], v116 offset:16384
	ds_read_b128 v[216:219], v116 offset:18432
	ds_read_b128 v[220:223], v114
	ds_read_b128 v[224:227], v114 offset:2048
	ds_read_b128 v[228:231], v116 offset:20480
	ds_read_b128 v[232:235], v117 offset:16384
	ds_read_b128 v[236:239], v114 offset:4096
	ds_read_b128 v[240:243], v115
	s_setprio 1
	s_waitcnt lgkmcnt(13)
	v_mfma_f32_16x16x32_bf16 v[94:97], v[152:155], v[160:163], v[94:97]
	v_mfma_f32_16x16x32_bf16 v[90:93], v[156:159], v[160:163], v[90:93]
	s_waitcnt lgkmcnt(11)
	v_mfma_f32_16x16x32_bf16 v[86:89], v[168:171], v[160:163], v[86:89]
	s_waitcnt lgkmcnt(10)
	v_mfma_f32_16x16x32_bf16 v[82:85], v[172:175], v[160:163], v[82:85]
	v_mfma_f32_16x16x32_bf16 v[78:81], v[152:155], v[164:167], v[78:81]
	v_mfma_f32_16x16x32_bf16 v[74:77], v[156:159], v[164:167], v[74:77]
	v_mfma_f32_16x16x32_bf16 v[62:65], v[168:171], v[164:167], v[62:65]
	v_mfma_f32_16x16x32_bf16 v[30:33], v[172:175], v[164:167], v[30:33]
	s_waitcnt lgkmcnt(9)
	v_mfma_f32_16x16x32_bf16 v[66:69], v[152:155], v[204:207], v[66:69]
	v_mfma_f32_16x16x32_bf16 v[38:41], v[156:159], v[204:207], v[38:41]
	v_mfma_f32_16x16x32_bf16 v[34:37], v[168:171], v[204:207], v[34:37]
	v_mfma_f32_16x16x32_bf16 v[18:21], v[172:175], v[204:207], v[18:21]
	s_waitcnt lgkmcnt(8)
	v_mfma_f32_16x16x32_bf16 v[14:17], v[152:155], v[208:211], v[14:17]
	v_mfma_f32_16x16x32_bf16 v[10:13], v[156:159], v[208:211], v[10:13]
	v_mfma_f32_16x16x32_bf16 v[6:9], v[168:171], v[208:211], v[6:9]
	v_mfma_f32_16x16x32_bf16 v[2:5], v[172:175], v[208:211], v[2:5]
	s_setprio 0
	s_waitcnt lgkmcnt(0)
	s_barrier
	s_add_i32 s4, s14, 0x80
	s_min_u32 s4, s4, 0x3c0
	s_lshl_b32 s4, s4, 1
	s_setprio 1
	v_mfma_f32_16x16x32_bf16 v[94:97], v[212:215], v[220:223], v[94:97]
	s_add_u32 m0, s15, 0x0
	v_lshl_add_u64 v[200:201], v[184:185], 0, s[4:5]
	global_load_lds_dwordx4 v[200:201], off
	v_mfma_f32_16x16x32_bf16 v[90:93], v[216:219], v[220:223], v[90:93]
	v_mfma_f32_16x16x32_bf16 v[86:89], v[228:231], v[220:223], v[86:89]
	s_add_u32 m0, s15, 0x1000
	v_lshl_add_u64 v[202:203], v[186:187], 0, s[4:5]
	global_load_lds_dwordx4 v[202:203], off
	v_mfma_f32_16x16x32_bf16 v[82:85], v[232:235], v[220:223], v[82:85]
	v_mfma_f32_16x16x32_bf16 v[78:81], v[212:215], v[224:227], v[78:81]
	s_add_u32 m0, s15, 0x2000
	v_lshl_add_u64 v[200:201], v[188:189], 0, s[4:5]
	global_load_lds_dwordx4 v[200:201], off
	v_mfma_f32_16x16x32_bf16 v[74:77], v[216:219], v[224:227], v[74:77]
	v_mfma_f32_16x16x32_bf16 v[62:65], v[228:231], v[224:227], v[62:65]
	s_add_u32 m0, s15, 0x3000
	v_lshl_add_u64 v[202:203], v[190:191], 0, s[4:5]
	global_load_lds_dwordx4 v[202:203], off
	v_mfma_f32_16x16x32_bf16 v[30:33], v[232:235], v[224:227], v[30:33]
	v_mfma_f32_16x16x32_bf16 v[66:69], v[212:215], v[236:239], v[66:69]
	s_add_u32 m0, s15, 0x4000
	v_lshl_add_u64 v[200:201], v[192:193], 0, s[4:5]
	global_load_lds_dwordx4 v[200:201], off
	v_mfma_f32_16x16x32_bf16 v[38:41], v[216:219], v[236:239], v[38:41]
	v_mfma_f32_16x16x32_bf16 v[34:37], v[228:231], v[236:239], v[34:37]
	s_add_u32 m0, s15, 0x5000
	v_lshl_add_u64 v[202:203], v[194:195], 0, s[4:5]
	global_load_lds_dwordx4 v[202:203], off
	v_mfma_f32_16x16x32_bf16 v[18:21], v[232:235], v[236:239], v[18:21]
	v_mfma_f32_16x16x32_bf16 v[14:17], v[212:215], v[240:243], v[14:17]
	s_add_u32 m0, s15, 0x6000
	v_lshl_add_u64 v[200:201], v[196:197], 0, s[4:5]
	global_load_lds_dwordx4 v[200:201], off
	v_mfma_f32_16x16x32_bf16 v[10:13], v[216:219], v[240:243], v[10:13]
	v_mfma_f32_16x16x32_bf16 v[6:9], v[228:231], v[240:243], v[6:9]
	s_add_u32 m0, s15, 0x7000
	v_lshl_add_u64 v[202:203], v[198:199], 0, s[4:5]
	global_load_lds_dwordx4 v[202:203], off
	v_mfma_f32_16x16x32_bf16 v[2:5], v[232:235], v[240:243], v[2:5]
	s_setprio 0
	s_waitcnt vmcnt(8)
	s_barrier
	ds_read_b128 v[152:155], v112 offset:49152
	ds_read_b128 v[156:159], v112 offset:51200
	ds_read_b128 v[160:163], v110 offset:32768
	ds_read_b128 v[164:167], v110 offset:34816
	ds_read_b128 v[168:171], v112 offset:53248
	ds_read_b128 v[172:175], v113 offset:49152
	ds_read_b128 v[204:207], v110 offset:36864
	ds_read_b128 v[208:211], v111 offset:32768
	ds_read_b128 v[212:215], v116 offset:49152
	ds_read_b128 v[216:219], v116 offset:51200
	ds_read_b128 v[220:223], v114 offset:32768
	ds_read_b128 v[224:227], v114 offset:34816
	ds_read_b128 v[228:231], v116 offset:53248
	ds_read_b128 v[232:235], v117 offset:49152
	ds_read_b128 v[236:239], v114 offset:36864
	ds_read_b128 v[240:243], v115 offset:32768
	s_setprio 1
	s_waitcnt lgkmcnt(13)
	v_mfma_f32_16x16x32_bf16 v[94:97], v[152:155], v[160:163], v[94:97]
	v_mfma_f32_16x16x32_bf16 v[90:93], v[156:159], v[160:163], v[90:93]
	s_waitcnt lgkmcnt(11)
	v_mfma_f32_16x16x32_bf16 v[86:89], v[168:171], v[160:163], v[86:89]
	s_waitcnt lgkmcnt(10)
	v_mfma_f32_16x16x32_bf16 v[82:85], v[172:175], v[160:163], v[82:85]
	v_mfma_f32_16x16x32_bf16 v[78:81], v[152:155], v[164:167], v[78:81]
	v_mfma_f32_16x16x32_bf16 v[74:77], v[156:159], v[164:167], v[74:77]
	v_mfma_f32_16x16x32_bf16 v[62:65], v[168:171], v[164:167], v[62:65]
	v_mfma_f32_16x16x32_bf16 v[30:33], v[172:175], v[164:167], v[30:33]
	s_waitcnt lgkmcnt(9)
	v_mfma_f32_16x16x32_bf16 v[66:69], v[152:155], v[204:207], v[66:69]
	v_mfma_f32_16x16x32_bf16 v[38:41], v[156:159], v[204:207], v[38:41]
	v_mfma_f32_16x16x32_bf16 v[34:37], v[168:171], v[204:207], v[34:37]
	v_mfma_f32_16x16x32_bf16 v[18:21], v[172:175], v[204:207], v[18:21]
	s_waitcnt lgkmcnt(8)
	v_mfma_f32_16x16x32_bf16 v[14:17], v[152:155], v[208:211], v[14:17]
	v_mfma_f32_16x16x32_bf16 v[10:13], v[156:159], v[208:211], v[10:13]
	v_mfma_f32_16x16x32_bf16 v[6:9], v[168:171], v[208:211], v[6:9]
	v_mfma_f32_16x16x32_bf16 v[2:5], v[172:175], v[208:211], v[2:5]
	s_setprio 0
	s_waitcnt lgkmcnt(0)
	s_barrier
	s_add_i32 s4, s14, 0xc0
	s_min_u32 s4, s4, 0x3c0
	s_lshl_b32 s4, s4, 1
	s_setprio 1
	v_mfma_f32_16x16x32_bf16 v[94:97], v[212:215], v[220:223], v[94:97]
	s_add_u32 m0, s15, 0x8000
	v_lshl_add_u64 v[200:201], v[184:185], 0, s[4:5]
	global_load_lds_dwordx4 v[200:201], off
	v_mfma_f32_16x16x32_bf16 v[90:93], v[216:219], v[220:223], v[90:93]
	v_mfma_f32_16x16x32_bf16 v[86:89], v[228:231], v[220:223], v[86:89]
	s_add_u32 m0, s15, 0x9000
	v_lshl_add_u64 v[202:203], v[186:187], 0, s[4:5]
	global_load_lds_dwordx4 v[202:203], off
	v_mfma_f32_16x16x32_bf16 v[82:85], v[232:235], v[220:223], v[82:85]
	v_mfma_f32_16x16x32_bf16 v[78:81], v[212:215], v[224:227], v[78:81]
	s_add_u32 m0, s15, 0xa000
	v_lshl_add_u64 v[200:201], v[188:189], 0, s[4:5]
	global_load_lds_dwordx4 v[200:201], off
	v_mfma_f32_16x16x32_bf16 v[74:77], v[216:219], v[224:227], v[74:77]
	v_mfma_f32_16x16x32_bf16 v[62:65], v[228:231], v[224:227], v[62:65]
	s_add_u32 m0, s15, 0xb000
	v_lshl_add_u64 v[202:203], v[190:191], 0, s[4:5]
	global_load_lds_dwordx4 v[202:203], off
	v_mfma_f32_16x16x32_bf16 v[30:33], v[232:235], v[224:227], v[30:33]
	v_mfma_f32_16x16x32_bf16 v[66:69], v[212:215], v[236:239], v[66:69]
	s_add_u32 m0, s15, 0xc000
	v_lshl_add_u64 v[200:201], v[192:193], 0, s[4:5]
	global_load_lds_dwordx4 v[200:201], off
	v_mfma_f32_16x16x32_bf16 v[38:41], v[216:219], v[236:239], v[38:41]
	v_mfma_f32_16x16x32_bf16 v[34:37], v[228:231], v[236:239], v[34:37]
	s_add_u32 m0, s15, 0xd000
	v_lshl_add_u64 v[202:203], v[194:195], 0, s[4:5]
	global_load_lds_dwordx4 v[202:203], off
	v_mfma_f32_16x16x32_bf16 v[18:21], v[232:235], v[236:239], v[18:21]
	v_mfma_f32_16x16x32_bf16 v[14:17], v[212:215], v[240:243], v[14:17]
	s_add_u32 m0, s15, 0xe000
	v_lshl_add_u64 v[200:201], v[196:197], 0, s[4:5]
	global_load_lds_dwordx4 v[200:201], off
	v_mfma_f32_16x16x32_bf16 v[10:13], v[216:219], v[240:243], v[10:13]
	v_mfma_f32_16x16x32_bf16 v[6:9], v[228:231], v[240:243], v[6:9]
	s_add_u32 m0, s15, 0xf000
	v_lshl_add_u64 v[202:203], v[198:199], 0, s[4:5]
	global_load_lds_dwordx4 v[202:203], off
	v_mfma_f32_16x16x32_bf16 v[2:5], v[232:235], v[240:243], v[2:5]
	s_setprio 0
	s_waitcnt vmcnt(8)
	s_barrier
	s_add_i32 s14, s14, 0x80
	s_add_i32 s13, s13, 2
	s_cmp_lt_u32 s13, 14
	s_cbranch_scc1 .Lglds2_12468
	s_waitcnt vmcnt(0)
	s_waitcnt vmcnt(0)
	v_or_b32_e32 v170, s12, v119
	v_add_lshl_u32 v98, v118, s11, 10
	v_readlane_b32 s12, v254, 8
	v_readlane_b32 s13, v254, 9
	v_readlane_b32 s14, v254, 10
	v_readlane_b32 s15, v254, 11
	v_readlane_b32 s16, v254, 12
	v_readlane_b32 s17, v254, 13
	v_readlane_b32 s18, v254, 14
	v_readlane_b32 s19, v254, 15
	v_readlane_b32 s20, v254, 16
	v_readlane_b32 s21, v254, 17
	v_readlane_b32 s22, v254, 18
	v_readlane_b32 s23, v254, 19
	v_readlane_b32 s24, v254, 20
	v_readlane_b32 s25, v254, 21
	v_readlane_b32 s26, v254, 22
	v_readlane_b32 s27, v254, 23
	v_lshlrev_b32_e32 v168, 2, v170
	v_mov_b32_e32 v169, v99
	v_lshlrev_b64 v[174:175], 2, v[98:99]
	v_lshl_add_u64 v[152:153], s[12:13], 0, v[174:175]
	v_lshl_add_u64 v[160:161], s[82:83], 0, v[174:175]
	v_lshl_add_u64 v[152:153], v[152:153], 0, v[168:169]
	v_lshl_add_u64 v[160:161], v[160:161], 0, v[168:169]
	global_load_dwordx4 v[120:123], v[152:153], off
	global_load_dwordx4 v[124:127], v[152:153], off offset:64
	global_load_dwordx4 v[128:131], v[152:153], off offset:128
	global_load_dwordx4 v[132:135], v[152:153], off offset:192
	v_or_b32_e32 v172, 0x4000, v98
	v_mov_b32_e32 v173, v99
	v_lshlrev_b64 v[174:175], 2, v[172:173]
	v_lshl_add_u64 v[154:155], s[12:13], 0, v[174:175]
	v_lshl_add_u64 v[162:163], s[82:83], 0, v[174:175]
	v_lshl_add_u64 v[154:155], v[154:155], 0, v[168:169]
	v_lshl_add_u64 v[162:163], v[162:163], 0, v[168:169]
	global_load_dwordx4 v[136:139], v[154:155], off
	global_load_dwordx4 v[140:143], v[154:155], off offset:64
	global_load_dwordx4 v[144:147], v[154:155], off offset:128
	global_load_dwordx4 v[148:151], v[154:155], off offset:192
	v_or_b32_e32 v172, 0x8000, v98
	v_mov_b32_e32 v173, v99
	v_lshlrev_b64 v[174:175], 2, v[172:173]
	v_lshl_add_u64 v[156:157], s[12:13], 0, v[174:175]
	v_lshl_add_u64 v[164:165], s[82:83], 0, v[174:175]
	v_lshl_add_u64 v[156:157], v[156:157], 0, v[168:169]
	v_lshl_add_u64 v[164:165], v[164:165], 0, v[168:169]
	global_load_dwordx4 v[22:25], v[156:157], off
	global_load_dwordx4 v[26:29], v[156:157], off offset:64
	global_load_dwordx4 v[42:45], v[156:157], off offset:128
	global_load_dwordx4 v[46:49], v[156:157], off offset:192
	v_or_b32_e32 v172, 0xc000, v98
	v_mov_b32_e32 v173, v99
	v_lshlrev_b64 v[174:175], 2, v[172:173]
	v_lshl_add_u64 v[158:159], s[12:13], 0, v[174:175]
	v_lshl_add_u64 v[166:167], s[82:83], 0, v[174:175]
	v_lshl_add_u64 v[158:159], v[158:159], 0, v[168:169]
	v_lshl_add_u64 v[166:167], v[166:167], 0, v[168:169]
	global_load_dwordx4 v[50:53], v[158:159], off
	global_load_dwordx4 v[54:57], v[158:159], off offset:64
	global_load_dwordx4 v[58:61], v[158:159], off offset:128
	global_load_dwordx4 v[70:73], v[158:159], off offset:192
	s_waitcnt vmcnt(15)
	v_pk_fma_f32 v[120:121], v[120:121], s[6:7], v[94:95] op_sel_hi:[1,0,1]
	v_pk_fma_f32 v[122:123], v[122:123], s[6:7], v[96:97] op_sel_hi:[1,0,1]
	s_waitcnt vmcnt(14)
	v_pk_fma_f32 v[124:125], v[124:125], s[6:7], v[90:91] op_sel_hi:[1,0,1]
	v_pk_fma_f32 v[126:127], v[126:127], s[6:7], v[92:93] op_sel_hi:[1,0,1]
	s_waitcnt vmcnt(13)
	v_pk_fma_f32 v[128:129], v[128:129], s[6:7], v[86:87] op_sel_hi:[1,0,1]
	v_pk_fma_f32 v[130:131], v[130:131], s[6:7], v[88:89] op_sel_hi:[1,0,1]
	s_waitcnt vmcnt(12)
	v_pk_fma_f32 v[132:133], v[132:133], s[6:7], v[82:83] op_sel_hi:[1,0,1]
	v_pk_fma_f32 v[134:135], v[134:135], s[6:7], v[84:85] op_sel_hi:[1,0,1]
	s_waitcnt vmcnt(11)
	v_pk_fma_f32 v[136:137], v[136:137], s[6:7], v[78:79] op_sel_hi:[1,0,1]
	v_pk_fma_f32 v[138:139], v[138:139], s[6:7], v[80:81] op_sel_hi:[1,0,1]
	s_waitcnt vmcnt(10)
	v_pk_fma_f32 v[140:141], v[140:141], s[6:7], v[74:75] op_sel_hi:[1,0,1]
	v_pk_fma_f32 v[142:143], v[142:143], s[6:7], v[76:77] op_sel_hi:[1,0,1]
	s_waitcnt vmcnt(9)
	v_pk_fma_f32 v[144:145], v[144:145], s[6:7], v[62:63] op_sel_hi:[1,0,1]
	v_pk_fma_f32 v[146:147], v[146:147], s[6:7], v[64:65] op_sel_hi:[1,0,1]
	s_waitcnt vmcnt(8)
	v_pk_fma_f32 v[148:149], v[148:149], s[6:7], v[30:31] op_sel_hi:[1,0,1]
	v_pk_fma_f32 v[150:151], v[150:151], s[6:7], v[32:33] op_sel_hi:[1,0,1]
	s_waitcnt vmcnt(7)
	v_pk_fma_f32 v[22:23], v[22:23], s[6:7], v[66:67] op_sel_hi:[1,0,1]
	v_pk_fma_f32 v[24:25], v[24:25], s[6:7], v[68:69] op_sel_hi:[1,0,1]
	s_waitcnt vmcnt(6)
	v_pk_fma_f32 v[26:27], v[26:27], s[6:7], v[38:39] op_sel_hi:[1,0,1]
	v_pk_fma_f32 v[28:29], v[28:29], s[6:7], v[40:41] op_sel_hi:[1,0,1]
	s_waitcnt vmcnt(5)
	v_pk_fma_f32 v[42:43], v[42:43], s[6:7], v[34:35] op_sel_hi:[1,0,1]
	v_pk_fma_f32 v[44:45], v[44:45], s[6:7], v[36:37] op_sel_hi:[1,0,1]
	s_waitcnt vmcnt(4)
	v_pk_fma_f32 v[46:47], v[46:47], s[6:7], v[18:19] op_sel_hi:[1,0,1]
	v_pk_fma_f32 v[48:49], v[48:49], s[6:7], v[20:21] op_sel_hi:[1,0,1]
	s_waitcnt vmcnt(3)
	v_pk_fma_f32 v[50:51], v[50:51], s[6:7], v[14:15] op_sel_hi:[1,0,1]
	v_pk_fma_f32 v[52:53], v[52:53], s[6:7], v[16:17] op_sel_hi:[1,0,1]
	s_waitcnt vmcnt(2)
	v_pk_fma_f32 v[54:55], v[54:55], s[6:7], v[10:11] op_sel_hi:[1,0,1]
	v_pk_fma_f32 v[56:57], v[56:57], s[6:7], v[12:13] op_sel_hi:[1,0,1]
	s_waitcnt vmcnt(1)
	v_pk_fma_f32 v[58:59], v[58:59], s[6:7], v[6:7] op_sel_hi:[1,0,1]
	v_pk_fma_f32 v[60:61], v[60:61], s[6:7], v[8:9] op_sel_hi:[1,0,1]
	s_waitcnt vmcnt(0)
	v_pk_fma_f32 v[70:71], v[70:71], s[6:7], v[2:3] op_sel_hi:[1,0,1]
	v_pk_fma_f32 v[72:73], v[72:73], s[6:7], v[4:5] op_sel_hi:[1,0,1]
	global_store_dwordx4 v[160:161], v[120:123], off
	global_store_dwordx4 v[160:161], v[124:127], off offset:64
	global_store_dwordx4 v[160:161], v[128:131], off offset:128
	global_store_dwordx4 v[160:161], v[132:135], off offset:192
	global_store_dwordx4 v[162:163], v[136:139], off
	global_store_dwordx4 v[162:163], v[140:143], off offset:64
	global_store_dwordx4 v[162:163], v[144:147], off offset:128
	global_store_dwordx4 v[162:163], v[148:151], off offset:192
	global_store_dwordx4 v[164:165], v[22:25], off
	global_store_dwordx4 v[164:165], v[26:29], off offset:64
	global_store_dwordx4 v[164:165], v[42:45], off offset:128
	global_store_dwordx4 v[164:165], v[46:49], off offset:192
	global_store_dwordx4 v[166:167], v[50:53], off
	global_store_dwordx4 v[166:167], v[54:57], off offset:64
	global_store_dwordx4 v[166:167], v[58:61], off offset:128
	global_store_dwordx4 v[166:167], v[70:73], off offset:192
	s_add_i32 s7, s7, s3
	s_cmpk_lt_u32 s7, 0x100
	s_cbranch_scc1 .LBB0_422

.Lglds2_14401:
	ds_read_b128 v[152:155], v112 offset:16384
	ds_read_b128 v[156:159], v112 offset:18432
	ds_read_b128 v[160:163], v110
	ds_read_b128 v[164:167], v110 offset:2048
	ds_read_b128 v[168:171], v112 offset:20480
	ds_read_b128 v[172:175], v113 offset:16384
	ds_read_b128 v[204:207], v110 offset:4096
	ds_read_b128 v[208:211], v111
	ds_read_b128 v[212:215], v116 offset:16384
	ds_read_b128 v[216:219], v116 offset:18432
	ds_read_b128 v[220:223], v114
	ds_read_b128 v[224:227], v114 offset:2048
	ds_read_b128 v[228:231], v116 offset:20480
	ds_read_b128 v[232:235], v117 offset:16384
	ds_read_b128 v[236:239], v114 offset:4096
	ds_read_b128 v[240:243], v115
	s_setprio 1
	s_waitcnt lgkmcnt(13)
	v_mfma_i32_16x16x64_i8 v[94:97], v[152:155], v[160:163], v[94:97]
	v_mfma_i32_16x16x64_i8 v[90:93], v[156:159], v[160:163], v[90:93]
	s_waitcnt lgkmcnt(11)
	v_mfma_i32_16x16x64_i8 v[86:89], v[168:171], v[160:163], v[86:89]
	s_waitcnt lgkmcnt(10)
	v_mfma_i32_16x16x64_i8 v[82:85], v[172:175], v[160:163], v[82:85]
	v_mfma_i32_16x16x64_i8 v[74:77], v[152:155], v[164:167], v[74:77]
	v_mfma_i32_16x16x64_i8 v[50:53], v[156:159], v[164:167], v[50:53]
	v_mfma_i32_16x16x64_i8 v[38:41], v[168:171], v[164:167], v[38:41]
	v_mfma_i32_16x16x64_i8 v[30:33], v[172:175], v[164:167], v[30:33]
	s_waitcnt lgkmcnt(9)
	v_mfma_i32_16x16x64_i8 v[34:37], v[152:155], v[204:207], v[34:37]
	v_mfma_i32_16x16x64_i8 v[26:29], v[156:159], v[204:207], v[26:29]
	v_mfma_i32_16x16x64_i8 v[22:25], v[168:171], v[204:207], v[22:25]
	v_mfma_i32_16x16x64_i8 v[18:21], v[172:175], v[204:207], v[18:21]
	s_waitcnt lgkmcnt(8)
	v_mfma_i32_16x16x64_i8 v[14:17], v[152:155], v[208:211], v[14:17]
	v_mfma_i32_16x16x64_i8 v[10:13], v[156:159], v[208:211], v[10:13]
	v_mfma_i32_16x16x64_i8 v[6:9], v[168:171], v[208:211], v[6:9]
	v_mfma_i32_16x16x64_i8 v[2:5], v[172:175], v[208:211], v[2:5]
	s_setprio 0
	s_waitcnt lgkmcnt(0)
	s_barrier
	s_add_i32 s4, s13, 0x80
	s_min_u32 s4, s4, 0x1c0
	s_lshl_b32 s4, s4, 1
	s_setprio 1
	v_mfma_i32_16x16x64_i8 v[94:97], v[212:215], v[220:223], v[94:97]
	s_add_u32 m0, s14, 0x0
	v_lshl_add_u64 v[200:201], v[184:185], 0, s[4:5]
	global_load_lds_dwordx4 v[200:201], off
	v_mfma_i32_16x16x64_i8 v[90:93], v[216:219], v[220:223], v[90:93]
	v_mfma_i32_16x16x64_i8 v[86:89], v[228:231], v[220:223], v[86:89]
	s_add_u32 m0, s14, 0x1000
	v_lshl_add_u64 v[202:203], v[186:187], 0, s[4:5]
	global_load_lds_dwordx4 v[202:203], off
	v_mfma_i32_16x16x64_i8 v[82:85], v[232:235], v[220:223], v[82:85]
	v_mfma_i32_16x16x64_i8 v[74:77], v[212:215], v[224:227], v[74:77]
	s_add_u32 m0, s14, 0x2000
	v_lshl_add_u64 v[200:201], v[188:189], 0, s[4:5]
	global_load_lds_dwordx4 v[200:201], off
	v_mfma_i32_16x16x64_i8 v[50:53], v[216:219], v[224:227], v[50:53]
	v_mfma_i32_16x16x64_i8 v[38:41], v[228:231], v[224:227], v[38:41]
	s_add_u32 m0, s14, 0x3000
	v_lshl_add_u64 v[202:203], v[190:191], 0, s[4:5]
	global_load_lds_dwordx4 v[202:203], off
	v_mfma_i32_16x16x64_i8 v[30:33], v[232:235], v[224:227], v[30:33]
	v_mfma_i32_16x16x64_i8 v[34:37], v[212:215], v[236:239], v[34:37]
	s_add_u32 m0, s14, 0x4000
	v_lshl_add_u64 v[200:201], v[192:193], 0, s[4:5]
	global_load_lds_dwordx4 v[200:201], off
	v_mfma_i32_16x16x64_i8 v[26:29], v[216:219], v[236:239], v[26:29]
	v_mfma_i32_16x16x64_i8 v[22:25], v[228:231], v[236:239], v[22:25]
	s_add_u32 m0, s14, 0x5000
	v_lshl_add_u64 v[202:203], v[194:195], 0, s[4:5]
	global_load_lds_dwordx4 v[202:203], off
	v_mfma_i32_16x16x64_i8 v[18:21], v[232:235], v[236:239], v[18:21]
	v_mfma_i32_16x16x64_i8 v[14:17], v[212:215], v[240:243], v[14:17]
	s_add_u32 m0, s14, 0x6000
	v_lshl_add_u64 v[200:201], v[196:197], 0, s[4:5]
	global_load_lds_dwordx4 v[200:201], off
	v_mfma_i32_16x16x64_i8 v[10:13], v[216:219], v[240:243], v[10:13]
	v_mfma_i32_16x16x64_i8 v[6:9], v[228:231], v[240:243], v[6:9]
	s_add_u32 m0, s14, 0x7000
	v_lshl_add_u64 v[202:203], v[198:199], 0, s[4:5]
	global_load_lds_dwordx4 v[202:203], off
	v_mfma_i32_16x16x64_i8 v[2:5], v[232:235], v[240:243], v[2:5]
	s_setprio 0
	s_waitcnt vmcnt(8)
	s_barrier
	ds_read_b128 v[152:155], v112 offset:49152
	ds_read_b128 v[156:159], v112 offset:51200
	ds_read_b128 v[160:163], v110 offset:32768
	ds_read_b128 v[164:167], v110 offset:34816
	ds_read_b128 v[168:171], v112 offset:53248
	ds_read_b128 v[172:175], v113 offset:49152
	ds_read_b128 v[204:207], v110 offset:36864
	ds_read_b128 v[208:211], v111 offset:32768
	ds_read_b128 v[212:215], v116 offset:49152
	ds_read_b128 v[216:219], v116 offset:51200
	ds_read_b128 v[220:223], v114 offset:32768
	ds_read_b128 v[224:227], v114 offset:34816
	ds_read_b128 v[228:231], v116 offset:53248
	ds_read_b128 v[232:235], v117 offset:49152
	ds_read_b128 v[236:239], v114 offset:36864
	ds_read_b128 v[240:243], v115 offset:32768
	s_setprio 1
	s_waitcnt lgkmcnt(13)
	v_mfma_i32_16x16x64_i8 v[94:97], v[152:155], v[160:163], v[94:97]
	v_mfma_i32_16x16x64_i8 v[90:93], v[156:159], v[160:163], v[90:93]
	s_waitcnt lgkmcnt(11)
	v_mfma_i32_16x16x64_i8 v[86:89], v[168:171], v[160:163], v[86:89]
	s_waitcnt lgkmcnt(10)
	v_mfma_i32_16x16x64_i8 v[82:85], v[172:175], v[160:163], v[82:85]
	v_mfma_i32_16x16x64_i8 v[74:77], v[152:155], v[164:167], v[74:77]
	v_mfma_i32_16x16x64_i8 v[50:53], v[156:159], v[164:167], v[50:53]
	v_mfma_i32_16x16x64_i8 v[38:41], v[168:171], v[164:167], v[38:41]
	v_mfma_i32_16x16x64_i8 v[30:33], v[172:175], v[164:167], v[30:33]
	s_waitcnt lgkmcnt(9)
	v_mfma_i32_16x16x64_i8 v[34:37], v[152:155], v[204:207], v[34:37]
	v_mfma_i32_16x16x64_i8 v[26:29], v[156:159], v[204:207], v[26:29]
	v_mfma_i32_16x16x64_i8 v[22:25], v[168:171], v[204:207], v[22:25]
	v_mfma_i32_16x16x64_i8 v[18:21], v[172:175], v[204:207], v[18:21]
	s_waitcnt lgkmcnt(8)
	v_mfma_i32_16x16x64_i8 v[14:17], v[152:155], v[208:211], v[14:17]
	v_mfma_i32_16x16x64_i8 v[10:13], v[156:159], v[208:211], v[10:13]
	v_mfma_i32_16x16x64_i8 v[6:9], v[168:171], v[208:211], v[6:9]
	v_mfma_i32_16x16x64_i8 v[2:5], v[172:175], v[208:211], v[2:5]
	s_setprio 0
	s_waitcnt lgkmcnt(0)
	s_barrier
	s_add_i32 s4, s13, 0xc0
	s_min_u32 s4, s4, 0x1c0
	s_lshl_b32 s4, s4, 1
	s_setprio 1
	v_mfma_i32_16x16x64_i8 v[94:97], v[212:215], v[220:223], v[94:97]
	s_add_u32 m0, s14, 0x8000
	v_lshl_add_u64 v[200:201], v[184:185], 0, s[4:5]
	global_load_lds_dwordx4 v[200:201], off
	v_mfma_i32_16x16x64_i8 v[90:93], v[216:219], v[220:223], v[90:93]
	v_mfma_i32_16x16x64_i8 v[86:89], v[228:231], v[220:223], v[86:89]
	s_add_u32 m0, s14, 0x9000
	v_lshl_add_u64 v[202:203], v[186:187], 0, s[4:5]
	global_load_lds_dwordx4 v[202:203], off
	v_mfma_i32_16x16x64_i8 v[82:85], v[232:235], v[220:223], v[82:85]
	v_mfma_i32_16x16x64_i8 v[74:77], v[212:215], v[224:227], v[74:77]
	s_add_u32 m0, s14, 0xa000
	v_lshl_add_u64 v[200:201], v[188:189], 0, s[4:5]
	global_load_lds_dwordx4 v[200:201], off
	v_mfma_i32_16x16x64_i8 v[50:53], v[216:219], v[224:227], v[50:53]
	v_mfma_i32_16x16x64_i8 v[38:41], v[228:231], v[224:227], v[38:41]
	s_add_u32 m0, s14, 0xb000
	v_lshl_add_u64 v[202:203], v[190:191], 0, s[4:5]
	global_load_lds_dwordx4 v[202:203], off
	v_mfma_i32_16x16x64_i8 v[30:33], v[232:235], v[224:227], v[30:33]
	v_mfma_i32_16x16x64_i8 v[34:37], v[212:215], v[236:239], v[34:37]
	s_add_u32 m0, s14, 0xc000
	v_lshl_add_u64 v[200:201], v[192:193], 0, s[4:5]
	global_load_lds_dwordx4 v[200:201], off
	v_mfma_i32_16x16x64_i8 v[26:29], v[216:219], v[236:239], v[26:29]
	v_mfma_i32_16x16x64_i8 v[22:25], v[228:231], v[236:239], v[22:25]
	s_add_u32 m0, s14, 0xd000
	v_lshl_add_u64 v[202:203], v[194:195], 0, s[4:5]
	global_load_lds_dwordx4 v[202:203], off
	v_mfma_i32_16x16x64_i8 v[18:21], v[232:235], v[236:239], v[18:21]
	v_mfma_i32_16x16x64_i8 v[14:17], v[212:215], v[240:243], v[14:17]
	s_add_u32 m0, s14, 0xe000
	v_lshl_add_u64 v[200:201], v[196:197], 0, s[4:5]
	global_load_lds_dwordx4 v[200:201], off
	v_mfma_i32_16x16x64_i8 v[10:13], v[216:219], v[240:243], v[10:13]
	v_mfma_i32_16x16x64_i8 v[6:9], v[228:231], v[240:243], v[6:9]
	s_add_u32 m0, s14, 0xf000
	v_lshl_add_u64 v[202:203], v[198:199], 0, s[4:5]
	global_load_lds_dwordx4 v[202:203], off
	v_mfma_i32_16x16x64_i8 v[2:5], v[232:235], v[240:243], v[2:5]
	s_setprio 0
	s_waitcnt vmcnt(8)
	s_barrier
	s_add_i32 s13, s13, 0x80
	s_add_i32 s12, s12, 2
	s_cmp_lt_u32 s12, 6
	s_cbranch_scc1 .Lglds2_14401
	s_waitcnt vmcnt(0)
	v_cvt_f32_i32_e32 v94, v94
	v_cvt_f32_i32_e32 v95, v95
	v_cvt_f32_i32_e32 v96, v96
	v_cvt_f32_i32_e32 v97, v97
	v_cvt_f32_i32_e32 v90, v90
	v_cvt_f32_i32_e32 v91, v91
	v_cvt_f32_i32_e32 v92, v92
	v_cvt_f32_i32_e32 v93, v93
	v_cvt_f32_i32_e32 v86, v86
	v_cvt_f32_i32_e32 v87, v87
	v_cvt_f32_i32_e32 v88, v88
	v_cvt_f32_i32_e32 v89, v89
	v_cvt_f32_i32_e32 v82, v82
	v_cvt_f32_i32_e32 v83, v83
	v_cvt_f32_i32_e32 v84, v84
	v_cvt_f32_i32_e32 v85, v85
	v_cvt_f32_i32_e32 v74, v74
	v_cvt_f32_i32_e32 v75, v75
	v_cvt_f32_i32_e32 v76, v76
	v_cvt_f32_i32_e32 v77, v77
	v_cvt_f32_i32_e32 v50, v50
	v_cvt_f32_i32_e32 v51, v51
	v_cvt_f32_i32_e32 v52, v52
	v_cvt_f32_i32_e32 v53, v53
	v_cvt_f32_i32_e32 v38, v38
	v_cvt_f32_i32_e32 v39, v39
	v_cvt_f32_i32_e32 v40, v40
	v_cvt_f32_i32_e32 v41, v41
	v_cvt_f32_i32_e32 v30, v30
	v_cvt_f32_i32_e32 v31, v31
	v_cvt_f32_i32_e32 v32, v32
	v_cvt_f32_i32_e32 v33, v33
	v_cvt_f32_i32_e32 v34, v34
	v_cvt_f32_i32_e32 v35, v35
	v_cvt_f32_i32_e32 v36, v36
	v_cvt_f32_i32_e32 v37, v37
	v_cvt_f32_i32_e32 v26, v26
	v_cvt_f32_i32_e32 v27, v27
	v_cvt_f32_i32_e32 v28, v28
	v_cvt_f32_i32_e32 v29, v29
	v_cvt_f32_i32_e32 v22, v22
	v_cvt_f32_i32_e32 v23, v23
	v_cvt_f32_i32_e32 v24, v24
	v_cvt_f32_i32_e32 v25, v25
	v_cvt_f32_i32_e32 v18, v18
	v_cvt_f32_i32_e32 v19, v19
	v_cvt_f32_i32_e32 v20, v20
	v_cvt_f32_i32_e32 v21, v21
	v_cvt_f32_i32_e32 v14, v14
	v_cvt_f32_i32_e32 v15, v15
	v_cvt_f32_i32_e32 v16, v16
	v_cvt_f32_i32_e32 v17, v17
	v_cvt_f32_i32_e32 v10, v10
	v_cvt_f32_i32_e32 v11, v11
	v_cvt_f32_i32_e32 v12, v12
	v_cvt_f32_i32_e32 v13, v13
	v_cvt_f32_i32_e32 v6, v6
	v_cvt_f32_i32_e32 v7, v7
	v_cvt_f32_i32_e32 v8, v8
	v_cvt_f32_i32_e32 v9, v9
	v_cvt_f32_i32_e32 v2, v2
	v_cvt_f32_i32_e32 v3, v3
	v_cvt_f32_i32_e32 v4, v4
	v_cvt_f32_i32_e32 v5, v5
	s_waitcnt vmcnt(0)
	v_add_u32_e32 v98, s10, v118
	v_or_b32_e32 v146, s11, v119
	v_lshl_add_u64 v[144:145], v[98:99], 2, s[68:69]
	v_lshlrev_b32_e32 v148, 2, v146
	global_load_dword v136, v[144:145], off
	global_load_dword v138, v[144:145], off offset:64
	global_load_dword v140, v[144:145], off offset:128
	global_load_dword v142, v[144:145], off offset:192
	global_load_dwordx4 v[120:123], v148, s[74:75]
	global_load_dwordx4 v[124:127], v148, s[74:75] offset:64
	global_load_dwordx4 v[128:131], v148, s[74:75] offset:128
	global_load_dwordx4 v[132:135], v148, s[74:75] offset:192
	v_lshlrev_b32_e32 v146, 1, v146
	v_mov_b32_e32 v147, v99
	v_lshlrev_b64 v[42:43], 12, v[98:99]
	v_lshl_add_u64 v[42:43], s[64:65], 0, v[42:43]
	v_lshl_add_u64 v[42:43], v[42:43], 0, v[146:147]
	v_or_b32_e32 v54, 16, v98
	v_mov_b32_e32 v55, v99
	v_lshlrev_b64 v[44:45], 12, v[54:55]
	v_lshl_add_u64 v[44:45], s[64:65], 0, v[44:45]
	v_lshl_add_u64 v[44:45], v[44:45], 0, v[146:147]
	v_or_b32_e32 v54, 32, v98
	v_mov_b32_e32 v55, v99
	v_lshlrev_b64 v[46:47], 12, v[54:55]
	v_lshl_add_u64 v[46:47], s[64:65], 0, v[46:47]
	v_lshl_add_u64 v[46:47], v[46:47], 0, v[146:147]
	v_or_b32_e32 v54, 48, v98
	v_mov_b32_e32 v55, v99
	v_lshlrev_b64 v[48:49], 12, v[54:55]
	v_lshl_add_u64 v[48:49], s[64:65], 0, v[48:49]
	v_lshl_add_u64 v[48:49], v[48:49], 0, v[146:147]
	s_waitcnt vmcnt(0)
	v_pk_mul_f32 v[94:95], v[136:137], v[94:95] op_sel_hi:[0,1]
	v_pk_mul_f32 v[96:97], v[136:137], v[96:97] op_sel_hi:[0,1]
	v_pk_mul_f32 v[94:95], v[120:121], v[94:95]
	v_pk_mul_f32 v[96:97], v[96:97], v[122:123]
	v_cvt_pk_bf16_f32 v94, v94, v95
	v_cvt_pk_bf16_f32 v95, v96, v97
	global_store_dwordx2 v[42:43], v[94:95], off
	v_pk_mul_f32 v[90:91], v[136:137], v[90:91] op_sel_hi:[0,1]
	v_pk_mul_f32 v[92:93], v[136:137], v[92:93] op_sel_hi:[0,1]
	v_pk_mul_f32 v[90:91], v[124:125], v[90:91]
	v_pk_mul_f32 v[92:93], v[92:93], v[126:127]
	v_cvt_pk_bf16_f32 v90, v90, v91
	v_cvt_pk_bf16_f32 v91, v92, v93
	global_store_dwordx2 v[42:43], v[90:91], off offset:32
	v_pk_mul_f32 v[86:87], v[136:137], v[86:87] op_sel_hi:[0,1]
	v_pk_mul_f32 v[88:89], v[136:137], v[88:89] op_sel_hi:[0,1]
	v_pk_mul_f32 v[86:87], v[128:129], v[86:87]
	v_pk_mul_f32 v[88:89], v[88:89], v[130:131]
	v_cvt_pk_bf16_f32 v86, v86, v87
	v_cvt_pk_bf16_f32 v87, v88, v89
	global_store_dwordx2 v[42:43], v[86:87], off offset:64
	v_pk_mul_f32 v[82:83], v[136:137], v[82:83] op_sel_hi:[0,1]
	v_pk_mul_f32 v[84:85], v[136:137], v[84:85] op_sel_hi:[0,1]
	v_pk_mul_f32 v[82:83], v[132:133], v[82:83]
	v_pk_mul_f32 v[84:85], v[84:85], v[134:135]
	v_cvt_pk_bf16_f32 v82, v82, v83
	v_cvt_pk_bf16_f32 v83, v84, v85
	global_store_dwordx2 v[42:43], v[82:83], off offset:96
	v_pk_mul_f32 v[74:75], v[138:139], v[74:75] op_sel_hi:[0,1]
	v_pk_mul_f32 v[76:77], v[138:139], v[76:77] op_sel_hi:[0,1]
	v_pk_mul_f32 v[74:75], v[120:121], v[74:75]
	v_pk_mul_f32 v[76:77], v[76:77], v[122:123]
	v_cvt_pk_bf16_f32 v74, v74, v75
	v_cvt_pk_bf16_f32 v75, v76, v77
	global_store_dwordx2 v[44:45], v[74:75], off
	v_pk_mul_f32 v[50:51], v[138:139], v[50:51] op_sel_hi:[0,1]
	v_pk_mul_f32 v[52:53], v[138:139], v[52:53] op_sel_hi:[0,1]
	v_pk_mul_f32 v[50:51], v[124:125], v[50:51]
	v_pk_mul_f32 v[52:53], v[52:53], v[126:127]
	v_cvt_pk_bf16_f32 v50, v50, v51
	v_cvt_pk_bf16_f32 v51, v52, v53
	global_store_dwordx2 v[44:45], v[50:51], off offset:32
	v_pk_mul_f32 v[38:39], v[138:139], v[38:39] op_sel_hi:[0,1]
	v_pk_mul_f32 v[40:41], v[138:139], v[40:41] op_sel_hi:[0,1]
	v_pk_mul_f32 v[38:39], v[128:129], v[38:39]
	v_pk_mul_f32 v[40:41], v[40:41], v[130:131]
	v_cvt_pk_bf16_f32 v38, v38, v39
	v_cvt_pk_bf16_f32 v39, v40, v41
	global_store_dwordx2 v[44:45], v[38:39], off offset:64
	v_pk_mul_f32 v[30:31], v[138:139], v[30:31] op_sel_hi:[0,1]
	v_pk_mul_f32 v[32:33], v[138:139], v[32:33] op_sel_hi:[0,1]
	v_pk_mul_f32 v[30:31], v[132:133], v[30:31]
	v_pk_mul_f32 v[32:33], v[32:33], v[134:135]
	v_cvt_pk_bf16_f32 v30, v30, v31
	v_cvt_pk_bf16_f32 v31, v32, v33
	global_store_dwordx2 v[44:45], v[30:31], off offset:96
	v_pk_mul_f32 v[34:35], v[140:141], v[34:35] op_sel_hi:[0,1]
	v_pk_mul_f32 v[36:37], v[140:141], v[36:37] op_sel_hi:[0,1]
	v_pk_mul_f32 v[34:35], v[120:121], v[34:35]
	v_pk_mul_f32 v[36:37], v[36:37], v[122:123]
	v_cvt_pk_bf16_f32 v34, v34, v35
	v_cvt_pk_bf16_f32 v35, v36, v37
	global_store_dwordx2 v[46:47], v[34:35], off
	v_pk_mul_f32 v[26:27], v[140:141], v[26:27] op_sel_hi:[0,1]
	v_pk_mul_f32 v[28:29], v[140:141], v[28:29] op_sel_hi:[0,1]
	v_pk_mul_f32 v[26:27], v[124:125], v[26:27]
	v_pk_mul_f32 v[28:29], v[28:29], v[126:127]
	v_cvt_pk_bf16_f32 v26, v26, v27
	v_cvt_pk_bf16_f32 v27, v28, v29
	global_store_dwordx2 v[46:47], v[26:27], off offset:32
	v_pk_mul_f32 v[22:23], v[140:141], v[22:23] op_sel_hi:[0,1]
	v_pk_mul_f32 v[24:25], v[140:141], v[24:25] op_sel_hi:[0,1]
	v_pk_mul_f32 v[22:23], v[128:129], v[22:23]
	v_pk_mul_f32 v[24:25], v[24:25], v[130:131]
	v_cvt_pk_bf16_f32 v22, v22, v23
	v_cvt_pk_bf16_f32 v23, v24, v25
	global_store_dwordx2 v[46:47], v[22:23], off offset:64
	v_pk_mul_f32 v[18:19], v[140:141], v[18:19] op_sel_hi:[0,1]
	v_pk_mul_f32 v[20:21], v[140:141], v[20:21] op_sel_hi:[0,1]
	v_pk_mul_f32 v[18:19], v[132:133], v[18:19]
	v_pk_mul_f32 v[20:21], v[20:21], v[134:135]
	v_cvt_pk_bf16_f32 v18, v18, v19
	v_cvt_pk_bf16_f32 v19, v20, v21
	global_store_dwordx2 v[46:47], v[18:19], off offset:96
	v_pk_mul_f32 v[14:15], v[142:143], v[14:15] op_sel_hi:[0,1]
	v_pk_mul_f32 v[16:17], v[142:143], v[16:17] op_sel_hi:[0,1]
	v_pk_mul_f32 v[14:15], v[120:121], v[14:15]
	v_pk_mul_f32 v[16:17], v[16:17], v[122:123]
	v_cvt_pk_bf16_f32 v14, v14, v15
	v_cvt_pk_bf16_f32 v15, v16, v17
	global_store_dwordx2 v[48:49], v[14:15], off
	v_pk_mul_f32 v[10:11], v[142:143], v[10:11] op_sel_hi:[0,1]
	v_pk_mul_f32 v[12:13], v[142:143], v[12:13] op_sel_hi:[0,1]
	v_pk_mul_f32 v[10:11], v[124:125], v[10:11]
	v_pk_mul_f32 v[12:13], v[12:13], v[126:127]
	v_cvt_pk_bf16_f32 v10, v10, v11
	v_cvt_pk_bf16_f32 v11, v12, v13
	global_store_dwordx2 v[48:49], v[10:11], off offset:32
	v_pk_mul_f32 v[6:7], v[142:143], v[6:7] op_sel_hi:[0,1]
	v_pk_mul_f32 v[8:9], v[142:143], v[8:9] op_sel_hi:[0,1]
	v_pk_mul_f32 v[6:7], v[128:129], v[6:7]
	v_pk_mul_f32 v[8:9], v[8:9], v[130:131]
	v_cvt_pk_bf16_f32 v6, v6, v7
	v_cvt_pk_bf16_f32 v7, v8, v9
	global_store_dwordx2 v[48:49], v[6:7], off offset:64
	v_pk_mul_f32 v[2:3], v[142:143], v[2:3] op_sel_hi:[0,1]
	v_pk_mul_f32 v[4:5], v[142:143], v[4:5] op_sel_hi:[0,1]
	v_pk_mul_f32 v[2:3], v[132:133], v[2:3]
	v_pk_mul_f32 v[4:5], v[4:5], v[134:135]
	v_cvt_pk_bf16_f32 v2, v2, v3
	v_cvt_pk_bf16_f32 v3, v4, v5
	global_store_dwordx2 v[48:49], v[2:3], off offset:96
	s_add_i32 s6, s6, s3
	s_cmpk_lt_u32 s6, 0x200
	s_cbranch_scc1 .LBB0_518

.Lglds2_22142:
	ds_read_b128 v[152:155], v112 offset:16384
	ds_read_b128 v[156:159], v112 offset:18432
	ds_read_b128 v[160:163], v110
	ds_read_b128 v[164:167], v110 offset:2048
	ds_read_b128 v[168:171], v112 offset:20480
	ds_read_b128 v[172:175], v113 offset:16384
	ds_read_b128 v[208:211], v110 offset:4096
	ds_read_b128 v[212:215], v111
	ds_read_b128 v[216:219], v116 offset:16384
	ds_read_b128 v[220:223], v116 offset:18432
	ds_read_b128 v[224:227], v114
	ds_read_b128 v[228:231], v114 offset:2048
	ds_read_b128 v[232:235], v116 offset:20480
	ds_read_b128 v[236:239], v117 offset:16384
	ds_read_b128 v[240:243], v114 offset:4096
	ds_read_b128 v[244:247], v115
	s_setprio 1
	s_waitcnt lgkmcnt(13)
	v_mfma_f32_16x16x32_bf16 v[94:97], v[152:155], v[160:163], v[94:97]
	v_mfma_f32_16x16x32_bf16 v[90:93], v[156:159], v[160:163], v[90:93]
	s_waitcnt lgkmcnt(11)
	v_mfma_f32_16x16x32_bf16 v[86:89], v[168:171], v[160:163], v[86:89]
	s_waitcnt lgkmcnt(10)
	v_mfma_f32_16x16x32_bf16 v[82:85], v[172:175], v[160:163], v[82:85]
	v_mfma_f32_16x16x32_bf16 v[54:57], v[152:155], v[164:167], v[54:57]
	v_mfma_f32_16x16x32_bf16 v[42:45], v[156:159], v[164:167], v[42:45]
	v_mfma_f32_16x16x32_bf16 v[38:41], v[168:171], v[164:167], v[38:41]
	v_mfma_f32_16x16x32_bf16 v[34:37], v[172:175], v[164:167], v[34:37]
	s_waitcnt lgkmcnt(9)
	v_mfma_f32_16x16x32_bf16 v[78:81], v[152:155], v[208:211], v[78:81]
	v_mfma_f32_16x16x32_bf16 v[74:77], v[156:159], v[208:211], v[74:77]
	v_mfma_f32_16x16x32_bf16 v[70:73], v[168:171], v[208:211], v[70:73]
	v_mfma_f32_16x16x32_bf16 v[66:69], v[172:175], v[208:211], v[66:69]
	s_waitcnt lgkmcnt(8)
	v_mfma_f32_16x16x32_bf16 v[62:65], v[152:155], v[212:215], v[62:65]
	v_mfma_f32_16x16x32_bf16 v[58:61], v[156:159], v[212:215], v[58:61]
	v_mfma_f32_16x16x32_bf16 v[50:53], v[168:171], v[212:215], v[50:53]
	v_mfma_f32_16x16x32_bf16 v[46:49], v[172:175], v[212:215], v[46:49]
	s_setprio 0
	s_waitcnt lgkmcnt(0)
	s_barrier
	s_add_i32 s4, s16, 0x80
	s_min_u32 s4, s4, 0x3c0
	s_lshl_b32 s4, s4, 1
	s_setprio 1
	v_mfma_f32_16x16x32_bf16 v[94:97], v[216:219], v[224:227], v[94:97]
	s_add_u32 m0, s17, 0x0
	v_lshl_add_u64 v[204:205], v[188:189], 0, s[4:5]
	global_load_lds_dwordx4 v[204:205], off
	v_mfma_f32_16x16x32_bf16 v[90:93], v[220:223], v[224:227], v[90:93]
	v_mfma_f32_16x16x32_bf16 v[86:89], v[232:235], v[224:227], v[86:89]
	s_add_u32 m0, s17, 0x1000
	v_lshl_add_u64 v[206:207], v[190:191], 0, s[4:5]
	global_load_lds_dwordx4 v[206:207], off
	v_mfma_f32_16x16x32_bf16 v[82:85], v[236:239], v[224:227], v[82:85]
	v_mfma_f32_16x16x32_bf16 v[54:57], v[216:219], v[228:231], v[54:57]
	s_add_u32 m0, s17, 0x2000
	v_lshl_add_u64 v[204:205], v[192:193], 0, s[4:5]
	global_load_lds_dwordx4 v[204:205], off
	v_mfma_f32_16x16x32_bf16 v[42:45], v[220:223], v[228:231], v[42:45]
	v_mfma_f32_16x16x32_bf16 v[38:41], v[232:235], v[228:231], v[38:41]
	s_add_u32 m0, s17, 0x3000
	v_lshl_add_u64 v[206:207], v[194:195], 0, s[4:5]
	global_load_lds_dwordx4 v[206:207], off
	v_mfma_f32_16x16x32_bf16 v[34:37], v[236:239], v[228:231], v[34:37]
	v_mfma_f32_16x16x32_bf16 v[78:81], v[216:219], v[240:243], v[78:81]
	s_add_u32 m0, s17, 0x4000
	v_lshl_add_u64 v[204:205], v[196:197], 0, s[4:5]
	global_load_lds_dwordx4 v[204:205], off
	v_mfma_f32_16x16x32_bf16 v[74:77], v[220:223], v[240:243], v[74:77]
	v_mfma_f32_16x16x32_bf16 v[70:73], v[232:235], v[240:243], v[70:73]
	s_add_u32 m0, s17, 0x5000
	v_lshl_add_u64 v[206:207], v[198:199], 0, s[4:5]
	global_load_lds_dwordx4 v[206:207], off
	v_mfma_f32_16x16x32_bf16 v[66:69], v[236:239], v[240:243], v[66:69]
	v_mfma_f32_16x16x32_bf16 v[62:65], v[216:219], v[244:247], v[62:65]
	s_add_u32 m0, s17, 0x6000
	v_lshl_add_u64 v[204:205], v[200:201], 0, s[4:5]
	global_load_lds_dwordx4 v[204:205], off
	v_mfma_f32_16x16x32_bf16 v[58:61], v[220:223], v[244:247], v[58:61]
	v_mfma_f32_16x16x32_bf16 v[50:53], v[232:235], v[244:247], v[50:53]
	s_add_u32 m0, s17, 0x7000
	v_lshl_add_u64 v[206:207], v[202:203], 0, s[4:5]
	global_load_lds_dwordx4 v[206:207], off
	v_mfma_f32_16x16x32_bf16 v[46:49], v[236:239], v[244:247], v[46:49]
	s_setprio 0
	s_waitcnt vmcnt(8)
	s_barrier
	ds_read_b128 v[152:155], v112 offset:49152
	ds_read_b128 v[156:159], v112 offset:51200
	ds_read_b128 v[160:163], v110 offset:32768
	ds_read_b128 v[164:167], v110 offset:34816
	ds_read_b128 v[168:171], v112 offset:53248
	ds_read_b128 v[172:175], v113 offset:49152
	ds_read_b128 v[208:211], v110 offset:36864
	ds_read_b128 v[212:215], v111 offset:32768
	ds_read_b128 v[216:219], v116 offset:49152
	ds_read_b128 v[220:223], v116 offset:51200
	ds_read_b128 v[224:227], v114 offset:32768
	ds_read_b128 v[228:231], v114 offset:34816
	ds_read_b128 v[232:235], v116 offset:53248
	ds_read_b128 v[236:239], v117 offset:49152
	ds_read_b128 v[240:243], v114 offset:36864
	ds_read_b128 v[244:247], v115 offset:32768
	s_setprio 1
	s_waitcnt lgkmcnt(13)
	v_mfma_f32_16x16x32_bf16 v[94:97], v[152:155], v[160:163], v[94:97]
	v_mfma_f32_16x16x32_bf16 v[90:93], v[156:159], v[160:163], v[90:93]
	s_waitcnt lgkmcnt(11)
	v_mfma_f32_16x16x32_bf16 v[86:89], v[168:171], v[160:163], v[86:89]
	s_waitcnt lgkmcnt(10)
	v_mfma_f32_16x16x32_bf16 v[82:85], v[172:175], v[160:163], v[82:85]
	v_mfma_f32_16x16x32_bf16 v[54:57], v[152:155], v[164:167], v[54:57]
	v_mfma_f32_16x16x32_bf16 v[42:45], v[156:159], v[164:167], v[42:45]
	v_mfma_f32_16x16x32_bf16 v[38:41], v[168:171], v[164:167], v[38:41]
	v_mfma_f32_16x16x32_bf16 v[34:37], v[172:175], v[164:167], v[34:37]
	s_waitcnt lgkmcnt(9)
	v_mfma_f32_16x16x32_bf16 v[78:81], v[152:155], v[208:211], v[78:81]
	v_mfma_f32_16x16x32_bf16 v[74:77], v[156:159], v[208:211], v[74:77]
	v_mfma_f32_16x16x32_bf16 v[70:73], v[168:171], v[208:211], v[70:73]
	v_mfma_f32_16x16x32_bf16 v[66:69], v[172:175], v[208:211], v[66:69]
	s_waitcnt lgkmcnt(8)
	v_mfma_f32_16x16x32_bf16 v[62:65], v[152:155], v[212:215], v[62:65]
	v_mfma_f32_16x16x32_bf16 v[58:61], v[156:159], v[212:215], v[58:61]
	v_mfma_f32_16x16x32_bf16 v[50:53], v[168:171], v[212:215], v[50:53]
	v_mfma_f32_16x16x32_bf16 v[46:49], v[172:175], v[212:215], v[46:49]
	s_setprio 0
	s_waitcnt lgkmcnt(0)
	s_barrier
	s_add_i32 s4, s16, 0xc0
	s_min_u32 s4, s4, 0x3c0
	s_lshl_b32 s4, s4, 1
	s_setprio 1
	v_mfma_f32_16x16x32_bf16 v[94:97], v[216:219], v[224:227], v[94:97]
	s_add_u32 m0, s17, 0x8000
	v_lshl_add_u64 v[204:205], v[188:189], 0, s[4:5]
	global_load_lds_dwordx4 v[204:205], off
	v_mfma_f32_16x16x32_bf16 v[90:93], v[220:223], v[224:227], v[90:93]
	v_mfma_f32_16x16x32_bf16 v[86:89], v[232:235], v[224:227], v[86:89]
	s_add_u32 m0, s17, 0x9000
	v_lshl_add_u64 v[206:207], v[190:191], 0, s[4:5]
	global_load_lds_dwordx4 v[206:207], off
	v_mfma_f32_16x16x32_bf16 v[82:85], v[236:239], v[224:227], v[82:85]
	v_mfma_f32_16x16x32_bf16 v[54:57], v[216:219], v[228:231], v[54:57]
	s_add_u32 m0, s17, 0xa000
	v_lshl_add_u64 v[204:205], v[192:193], 0, s[4:5]
	global_load_lds_dwordx4 v[204:205], off
	v_mfma_f32_16x16x32_bf16 v[42:45], v[220:223], v[228:231], v[42:45]
	v_mfma_f32_16x16x32_bf16 v[38:41], v[232:235], v[228:231], v[38:41]
	s_add_u32 m0, s17, 0xb000
	v_lshl_add_u64 v[206:207], v[194:195], 0, s[4:5]
	global_load_lds_dwordx4 v[206:207], off
	v_mfma_f32_16x16x32_bf16 v[34:37], v[236:239], v[228:231], v[34:37]
	v_mfma_f32_16x16x32_bf16 v[78:81], v[216:219], v[240:243], v[78:81]
	s_add_u32 m0, s17, 0xc000
	v_lshl_add_u64 v[204:205], v[196:197], 0, s[4:5]
	global_load_lds_dwordx4 v[204:205], off
	v_mfma_f32_16x16x32_bf16 v[74:77], v[220:223], v[240:243], v[74:77]
	v_mfma_f32_16x16x32_bf16 v[70:73], v[232:235], v[240:243], v[70:73]
	s_add_u32 m0, s17, 0xd000
	v_lshl_add_u64 v[206:207], v[198:199], 0, s[4:5]
	global_load_lds_dwordx4 v[206:207], off
	v_mfma_f32_16x16x32_bf16 v[66:69], v[236:239], v[240:243], v[66:69]
	v_mfma_f32_16x16x32_bf16 v[62:65], v[216:219], v[244:247], v[62:65]
	s_add_u32 m0, s17, 0xe000
	v_lshl_add_u64 v[204:205], v[200:201], 0, s[4:5]
	global_load_lds_dwordx4 v[204:205], off
	v_mfma_f32_16x16x32_bf16 v[58:61], v[220:223], v[244:247], v[58:61]
	v_mfma_f32_16x16x32_bf16 v[50:53], v[232:235], v[244:247], v[50:53]
	s_add_u32 m0, s17, 0xf000
	v_lshl_add_u64 v[206:207], v[202:203], 0, s[4:5]
	global_load_lds_dwordx4 v[206:207], off
	v_mfma_f32_16x16x32_bf16 v[46:49], v[236:239], v[244:247], v[46:49]
	s_setprio 0
	s_waitcnt vmcnt(8)
	s_barrier
	s_add_i32 s16, s16, 0x80
	s_add_i32 s15, s15, 2
	s_cmp_lt_u32 s15, 14
	s_cbranch_scc1 .Lglds2_22142
	s_waitcnt vmcnt(0)
	s_waitcnt vmcnt(7)
	v_or_b32_e32 v2, s14, v119
	s_waitcnt vmcnt(5)
	v_add_u32_e32 v10, s13, v118
	v_mov_b64_e32 v[4:5], s[64:65]
	v_ashrrev_i32_e32 v3, 31, v2
	v_mad_i64_i32 v[6:7], s[14:15], v10, s12, v[4:5]
	v_lshlrev_b64 v[2:3], 1, v[2:3]
	v_lshl_add_u64 v[6:7], v[6:7], 0, v[2:3]
	v_cvt_pk_bf16_f32 v8, v94, v95
	v_cvt_pk_bf16_f32 v9, v96, v97
	global_store_dwordx2 v[6:7], v[8:9], off
	v_cvt_pk_bf16_f32 v8, v90, v91
	v_cvt_pk_bf16_f32 v9, v92, v93
	global_store_dwordx2 v[6:7], v[8:9], off offset:32
	v_cvt_pk_bf16_f32 v8, v86, v87
	v_cvt_pk_bf16_f32 v9, v88, v89
	global_store_dwordx2 v[6:7], v[8:9], off offset:64
	v_cvt_pk_bf16_f32 v8, v82, v83
	v_cvt_pk_bf16_f32 v9, v84, v85
	global_store_dwordx2 v[6:7], v[8:9], off offset:96
	v_or_b32_e32 v6, 16, v10
	v_mad_i64_i32 v[6:7], s[14:15], v6, s12, v[4:5]
	v_lshl_add_u64 v[6:7], v[6:7], 0, v[2:3]
	v_cvt_pk_bf16_f32 v8, v54, v55
	v_cvt_pk_bf16_f32 v9, v56, v57
	global_store_dwordx2 v[6:7], v[8:9], off
	v_cvt_pk_bf16_f32 v8, v42, v43
	v_cvt_pk_bf16_f32 v9, v44, v45
	global_store_dwordx2 v[6:7], v[8:9], off offset:32
	v_cvt_pk_bf16_f32 v8, v38, v39
	v_cvt_pk_bf16_f32 v9, v40, v41
	global_store_dwordx2 v[6:7], v[8:9], off offset:64
	v_cvt_pk_bf16_f32 v8, v34, v35
	v_cvt_pk_bf16_f32 v9, v36, v37
	global_store_dwordx2 v[6:7], v[8:9], off offset:96
	v_or_b32_e32 v6, 32, v10
	v_mad_i64_i32 v[6:7], s[14:15], v6, s12, v[4:5]
	v_lshl_add_u64 v[6:7], v[6:7], 0, v[2:3]
	v_cvt_pk_bf16_f32 v8, v78, v79
	v_cvt_pk_bf16_f32 v9, v80, v81
	global_store_dwordx2 v[6:7], v[8:9], off
	v_cvt_pk_bf16_f32 v8, v74, v75
	v_cvt_pk_bf16_f32 v9, v76, v77
	global_store_dwordx2 v[6:7], v[8:9], off offset:32
	v_cvt_pk_bf16_f32 v8, v70, v71
	v_cvt_pk_bf16_f32 v9, v72, v73
	global_store_dwordx2 v[6:7], v[8:9], off offset:64
	v_cvt_pk_bf16_f32 v8, v66, v67
	v_cvt_pk_bf16_f32 v9, v68, v69
	global_store_dwordx2 v[6:7], v[8:9], off offset:96
	v_or_b32_e32 v6, 48, v10
	v_mad_i64_i32 v[4:5], s[14:15], v6, s12, v[4:5]
	v_lshl_add_u64 v[2:3], v[4:5], 0, v[2:3]
	v_cvt_pk_bf16_f32 v4, v62, v63
	v_cvt_pk_bf16_f32 v5, v64, v65
	global_store_dwordx2 v[2:3], v[4:5], off
	v_cvt_pk_bf16_f32 v4, v58, v59
	v_cvt_pk_bf16_f32 v5, v60, v61
	global_store_dwordx2 v[2:3], v[4:5], off offset:32
	v_cvt_pk_bf16_f32 v4, v50, v51
	v_cvt_pk_bf16_f32 v5, v52, v53
	s_add_i32 s3, s3, s2
	global_store_dwordx2 v[2:3], v[4:5], off offset:64
	v_cvt_pk_bf16_f32 v4, v46, v47
	v_cvt_pk_bf16_f32 v5, v48, v49
	s_cmpk_lt_u32 s3, 0x280
	global_store_dwordx2 v[2:3], v[4:5], off offset:96
	s_cbranch_scc1 .LBB0_664

.Lglds2_26323:
	ds_read_b128 v[152:155], v111 offset:16384
	ds_read_b128 v[156:159], v111 offset:18432
	ds_read_b128 v[160:163], v109
	ds_read_b128 v[164:167], v109 offset:2048
	ds_read_b128 v[168:171], v111 offset:20480
	ds_read_b128 v[172:175], v112 offset:16384
	ds_read_b128 v[208:211], v109 offset:4096
	ds_read_b128 v[212:215], v110
	ds_read_b128 v[216:219], v115 offset:16384
	ds_read_b128 v[220:223], v115 offset:18432
	ds_read_b128 v[224:227], v113
	ds_read_b128 v[228:231], v113 offset:2048
	ds_read_b128 v[232:235], v115 offset:20480
	ds_read_b128 v[236:239], v116 offset:16384
	ds_read_b128 v[240:243], v113 offset:4096
	ds_read_b128 v[244:247], v114
	s_setprio 1
	s_waitcnt lgkmcnt(13)
	v_mfma_f32_16x16x32_bf16 v[92:95], v[152:155], v[160:163], v[92:95]
	v_mfma_f32_16x16x32_bf16 v[88:91], v[156:159], v[160:163], v[88:91]
	s_waitcnt lgkmcnt(11)
	v_mfma_f32_16x16x32_bf16 v[84:87], v[168:171], v[160:163], v[84:87]
	s_waitcnt lgkmcnt(10)
	v_mfma_f32_16x16x32_bf16 v[80:83], v[172:175], v[160:163], v[80:83]
	v_mfma_f32_16x16x32_bf16 v[76:79], v[152:155], v[164:167], v[76:79]
	v_mfma_f32_16x16x32_bf16 v[72:75], v[156:159], v[164:167], v[72:75]
	v_mfma_f32_16x16x32_bf16 v[60:63], v[168:171], v[164:167], v[60:63]
	v_mfma_f32_16x16x32_bf16 v[28:31], v[172:175], v[164:167], v[28:31]
	s_waitcnt lgkmcnt(9)
	v_mfma_f32_16x16x32_bf16 v[64:67], v[152:155], v[208:211], v[64:67]
	v_mfma_f32_16x16x32_bf16 v[36:39], v[156:159], v[208:211], v[36:39]
	v_mfma_f32_16x16x32_bf16 v[32:35], v[168:171], v[208:211], v[32:35]
	v_mfma_f32_16x16x32_bf16 v[16:19], v[172:175], v[208:211], v[16:19]
	s_waitcnt lgkmcnt(8)
	v_mfma_f32_16x16x32_bf16 v[12:15], v[152:155], v[212:215], v[12:15]
	v_mfma_f32_16x16x32_bf16 v[8:11], v[156:159], v[212:215], v[8:11]
	v_mfma_f32_16x16x32_bf16 v[4:7], v[168:171], v[212:215], v[4:7]
	v_mfma_f32_16x16x32_bf16 v[0:3], v[172:175], v[212:215], v[0:3]
	s_setprio 0
	s_waitcnt lgkmcnt(0)
	s_barrier
	s_add_i32 s4, s14, 0x80
	s_min_u32 s4, s4, 0x3c0
	s_lshl_b32 s4, s4, 1
	s_setprio 1
	v_mfma_f32_16x16x32_bf16 v[92:95], v[216:219], v[224:227], v[92:95]
	s_add_u32 m0, s15, 0x0
	v_lshl_add_u64 v[204:205], v[188:189], 0, s[4:5]
	global_load_lds_dwordx4 v[204:205], off
	v_mfma_f32_16x16x32_bf16 v[88:91], v[220:223], v[224:227], v[88:91]
	v_mfma_f32_16x16x32_bf16 v[84:87], v[232:235], v[224:227], v[84:87]
	s_add_u32 m0, s15, 0x1000
	v_lshl_add_u64 v[206:207], v[190:191], 0, s[4:5]
	global_load_lds_dwordx4 v[206:207], off
	v_mfma_f32_16x16x32_bf16 v[80:83], v[236:239], v[224:227], v[80:83]
	v_mfma_f32_16x16x32_bf16 v[76:79], v[216:219], v[228:231], v[76:79]
	s_add_u32 m0, s15, 0x2000
	v_lshl_add_u64 v[204:205], v[192:193], 0, s[4:5]
	global_load_lds_dwordx4 v[204:205], off
	v_mfma_f32_16x16x32_bf16 v[72:75], v[220:223], v[228:231], v[72:75]
	v_mfma_f32_16x16x32_bf16 v[60:63], v[232:235], v[228:231], v[60:63]
	s_add_u32 m0, s15, 0x3000
	v_lshl_add_u64 v[206:207], v[194:195], 0, s[4:5]
	global_load_lds_dwordx4 v[206:207], off
	v_mfma_f32_16x16x32_bf16 v[28:31], v[236:239], v[228:231], v[28:31]
	v_mfma_f32_16x16x32_bf16 v[64:67], v[216:219], v[240:243], v[64:67]
	s_add_u32 m0, s15, 0x4000
	v_lshl_add_u64 v[204:205], v[196:197], 0, s[4:5]
	global_load_lds_dwordx4 v[204:205], off
	v_mfma_f32_16x16x32_bf16 v[36:39], v[220:223], v[240:243], v[36:39]
	v_mfma_f32_16x16x32_bf16 v[32:35], v[232:235], v[240:243], v[32:35]
	s_add_u32 m0, s15, 0x5000
	v_lshl_add_u64 v[206:207], v[198:199], 0, s[4:5]
	global_load_lds_dwordx4 v[206:207], off
	v_mfma_f32_16x16x32_bf16 v[16:19], v[236:239], v[240:243], v[16:19]
	v_mfma_f32_16x16x32_bf16 v[12:15], v[216:219], v[244:247], v[12:15]
	s_add_u32 m0, s15, 0x6000
	v_lshl_add_u64 v[204:205], v[200:201], 0, s[4:5]
	global_load_lds_dwordx4 v[204:205], off
	v_mfma_f32_16x16x32_bf16 v[8:11], v[220:223], v[244:247], v[8:11]
	v_mfma_f32_16x16x32_bf16 v[4:7], v[232:235], v[244:247], v[4:7]
	s_add_u32 m0, s15, 0x7000
	v_lshl_add_u64 v[206:207], v[202:203], 0, s[4:5]
	global_load_lds_dwordx4 v[206:207], off
	v_mfma_f32_16x16x32_bf16 v[0:3], v[236:239], v[244:247], v[0:3]
	s_setprio 0
	s_waitcnt vmcnt(8)
	s_barrier
	ds_read_b128 v[152:155], v111 offset:49152
	ds_read_b128 v[156:159], v111 offset:51200
	ds_read_b128 v[160:163], v109 offset:32768
	ds_read_b128 v[164:167], v109 offset:34816
	ds_read_b128 v[168:171], v111 offset:53248
	ds_read_b128 v[172:175], v112 offset:49152
	ds_read_b128 v[208:211], v109 offset:36864
	ds_read_b128 v[212:215], v110 offset:32768
	ds_read_b128 v[216:219], v115 offset:49152
	ds_read_b128 v[220:223], v115 offset:51200
	ds_read_b128 v[224:227], v113 offset:32768
	ds_read_b128 v[228:231], v113 offset:34816
	ds_read_b128 v[232:235], v115 offset:53248
	ds_read_b128 v[236:239], v116 offset:49152
	ds_read_b128 v[240:243], v113 offset:36864
	ds_read_b128 v[244:247], v114 offset:32768
	s_setprio 1
	s_waitcnt lgkmcnt(13)
	v_mfma_f32_16x16x32_bf16 v[92:95], v[152:155], v[160:163], v[92:95]
	v_mfma_f32_16x16x32_bf16 v[88:91], v[156:159], v[160:163], v[88:91]
	s_waitcnt lgkmcnt(11)
	v_mfma_f32_16x16x32_bf16 v[84:87], v[168:171], v[160:163], v[84:87]
	s_waitcnt lgkmcnt(10)
	v_mfma_f32_16x16x32_bf16 v[80:83], v[172:175], v[160:163], v[80:83]
	v_mfma_f32_16x16x32_bf16 v[76:79], v[152:155], v[164:167], v[76:79]
	v_mfma_f32_16x16x32_bf16 v[72:75], v[156:159], v[164:167], v[72:75]
	v_mfma_f32_16x16x32_bf16 v[60:63], v[168:171], v[164:167], v[60:63]
	v_mfma_f32_16x16x32_bf16 v[28:31], v[172:175], v[164:167], v[28:31]
	s_waitcnt lgkmcnt(9)
	v_mfma_f32_16x16x32_bf16 v[64:67], v[152:155], v[208:211], v[64:67]
	v_mfma_f32_16x16x32_bf16 v[36:39], v[156:159], v[208:211], v[36:39]
	v_mfma_f32_16x16x32_bf16 v[32:35], v[168:171], v[208:211], v[32:35]
	v_mfma_f32_16x16x32_bf16 v[16:19], v[172:175], v[208:211], v[16:19]
	s_waitcnt lgkmcnt(8)
	v_mfma_f32_16x16x32_bf16 v[12:15], v[152:155], v[212:215], v[12:15]
	v_mfma_f32_16x16x32_bf16 v[8:11], v[156:159], v[212:215], v[8:11]
	v_mfma_f32_16x16x32_bf16 v[4:7], v[168:171], v[212:215], v[4:7]
	v_mfma_f32_16x16x32_bf16 v[0:3], v[172:175], v[212:215], v[0:3]
	s_setprio 0
	s_waitcnt lgkmcnt(0)
	s_barrier
	s_add_i32 s4, s14, 0xc0
	s_min_u32 s4, s4, 0x3c0
	s_lshl_b32 s4, s4, 1
	s_setprio 1
	v_mfma_f32_16x16x32_bf16 v[92:95], v[216:219], v[224:227], v[92:95]
	s_add_u32 m0, s15, 0x8000
	v_lshl_add_u64 v[204:205], v[188:189], 0, s[4:5]
	global_load_lds_dwordx4 v[204:205], off
	v_mfma_f32_16x16x32_bf16 v[88:91], v[220:223], v[224:227], v[88:91]
	v_mfma_f32_16x16x32_bf16 v[84:87], v[232:235], v[224:227], v[84:87]
	s_add_u32 m0, s15, 0x9000
	v_lshl_add_u64 v[206:207], v[190:191], 0, s[4:5]
	global_load_lds_dwordx4 v[206:207], off
	v_mfma_f32_16x16x32_bf16 v[80:83], v[236:239], v[224:227], v[80:83]
	v_mfma_f32_16x16x32_bf16 v[76:79], v[216:219], v[228:231], v[76:79]
	s_add_u32 m0, s15, 0xa000
	v_lshl_add_u64 v[204:205], v[192:193], 0, s[4:5]
	global_load_lds_dwordx4 v[204:205], off
	v_mfma_f32_16x16x32_bf16 v[72:75], v[220:223], v[228:231], v[72:75]
	v_mfma_f32_16x16x32_bf16 v[60:63], v[232:235], v[228:231], v[60:63]
	s_add_u32 m0, s15, 0xb000
	v_lshl_add_u64 v[206:207], v[194:195], 0, s[4:5]
	global_load_lds_dwordx4 v[206:207], off
	v_mfma_f32_16x16x32_bf16 v[28:31], v[236:239], v[228:231], v[28:31]
	v_mfma_f32_16x16x32_bf16 v[64:67], v[216:219], v[240:243], v[64:67]
	s_add_u32 m0, s15, 0xc000
	v_lshl_add_u64 v[204:205], v[196:197], 0, s[4:5]
	global_load_lds_dwordx4 v[204:205], off
	v_mfma_f32_16x16x32_bf16 v[36:39], v[220:223], v[240:243], v[36:39]
	v_mfma_f32_16x16x32_bf16 v[32:35], v[232:235], v[240:243], v[32:35]
	s_add_u32 m0, s15, 0xd000
	v_lshl_add_u64 v[206:207], v[198:199], 0, s[4:5]
	global_load_lds_dwordx4 v[206:207], off
	v_mfma_f32_16x16x32_bf16 v[16:19], v[236:239], v[240:243], v[16:19]
	v_mfma_f32_16x16x32_bf16 v[12:15], v[216:219], v[244:247], v[12:15]
	s_add_u32 m0, s15, 0xe000
	v_lshl_add_u64 v[204:205], v[200:201], 0, s[4:5]
	global_load_lds_dwordx4 v[204:205], off
	v_mfma_f32_16x16x32_bf16 v[8:11], v[220:223], v[244:247], v[8:11]
	v_mfma_f32_16x16x32_bf16 v[4:7], v[232:235], v[244:247], v[4:7]
	s_add_u32 m0, s15, 0xf000
	v_lshl_add_u64 v[206:207], v[202:203], 0, s[4:5]
	global_load_lds_dwordx4 v[206:207], off
	v_mfma_f32_16x16x32_bf16 v[0:3], v[236:239], v[244:247], v[0:3]
	s_setprio 0
	s_waitcnt vmcnt(8)
	s_barrier
	s_add_i32 s14, s14, 0x80
	s_add_i32 s13, s13, 2
	s_cmp_lt_u32 s13, 14
	s_cbranch_scc1 .Lglds2_26323
	s_waitcnt vmcnt(0)
	s_waitcnt vmcnt(0)
	v_or_b32_e32 v170, s12, v118
	v_add_lshl_u32 v96, v117, s11, 10
	v_readlane_b32 s12, v254, 24
	v_readlane_b32 s16, v254, 28
	v_readlane_b32 s17, v254, 29
	v_readlane_b32 s13, v254, 25
	v_readlane_b32 s14, v254, 26
	v_readlane_b32 s15, v254, 27
	v_readlane_b32 s18, v254, 30
	v_readlane_b32 s19, v254, 31
	v_readlane_b32 s20, v254, 32
	v_readlane_b32 s21, v254, 33
	v_readlane_b32 s22, v254, 34
	v_readlane_b32 s23, v254, 35
	v_readlane_b32 s24, v254, 36
	v_readlane_b32 s25, v254, 37
	v_readlane_b32 s26, v254, 38
	v_readlane_b32 s27, v254, 39
	v_lshlrev_b32_e32 v168, 2, v170
	v_mov_b32_e32 v169, v97
	v_lshlrev_b64 v[174:175], 2, v[96:97]
	v_lshl_add_u64 v[152:153], s[16:17], 0, v[174:175]
	v_lshl_add_u64 v[160:161], s[82:83], 0, v[174:175]
	v_lshl_add_u64 v[152:153], v[152:153], 0, v[168:169]
	v_lshl_add_u64 v[160:161], v[160:161], 0, v[168:169]
	global_load_dwordx4 v[120:123], v[152:153], off
	global_load_dwordx4 v[124:127], v[152:153], off offset:64
	global_load_dwordx4 v[128:131], v[152:153], off offset:128
	global_load_dwordx4 v[132:135], v[152:153], off offset:192
	v_or_b32_e32 v172, 0x4000, v96
	v_mov_b32_e32 v173, v97
	v_lshlrev_b64 v[174:175], 2, v[172:173]
	v_lshl_add_u64 v[154:155], s[16:17], 0, v[174:175]
	v_lshl_add_u64 v[162:163], s[82:83], 0, v[174:175]
	v_lshl_add_u64 v[154:155], v[154:155], 0, v[168:169]
	v_lshl_add_u64 v[162:163], v[162:163], 0, v[168:169]
	global_load_dwordx4 v[136:139], v[154:155], off
	global_load_dwordx4 v[140:143], v[154:155], off offset:64
	global_load_dwordx4 v[144:147], v[154:155], off offset:128
	global_load_dwordx4 v[148:151], v[154:155], off offset:192
	v_or_b32_e32 v172, 0x8000, v96
	v_mov_b32_e32 v173, v97
	v_lshlrev_b64 v[174:175], 2, v[172:173]
	v_lshl_add_u64 v[156:157], s[16:17], 0, v[174:175]
	v_lshl_add_u64 v[164:165], s[82:83], 0, v[174:175]
	v_lshl_add_u64 v[156:157], v[156:157], 0, v[168:169]
	v_lshl_add_u64 v[164:165], v[164:165], 0, v[168:169]
	global_load_dwordx4 v[20:23], v[156:157], off
	global_load_dwordx4 v[24:27], v[156:157], off offset:64
	global_load_dwordx4 v[40:43], v[156:157], off offset:128
	global_load_dwordx4 v[44:47], v[156:157], off offset:192
	v_or_b32_e32 v172, 0xc000, v96
	v_mov_b32_e32 v173, v97
	v_lshlrev_b64 v[174:175], 2, v[172:173]
	v_lshl_add_u64 v[158:159], s[16:17], 0, v[174:175]
	v_lshl_add_u64 v[166:167], s[82:83], 0, v[174:175]
	v_lshl_add_u64 v[158:159], v[158:159], 0, v[168:169]
	v_lshl_add_u64 v[166:167], v[166:167], 0, v[168:169]
	global_load_dwordx4 v[48:51], v[158:159], off
	global_load_dwordx4 v[52:55], v[158:159], off offset:64
	global_load_dwordx4 v[56:59], v[158:159], off offset:128
	global_load_dwordx4 v[68:71], v[158:159], off offset:192
	s_waitcnt vmcnt(15)
	v_pk_fma_f32 v[120:121], v[120:121], s[6:7], v[92:93] op_sel_hi:[1,0,1]
	v_pk_fma_f32 v[122:123], v[122:123], s[6:7], v[94:95] op_sel_hi:[1,0,1]
	s_waitcnt vmcnt(14)
	v_pk_fma_f32 v[124:125], v[124:125], s[6:7], v[88:89] op_sel_hi:[1,0,1]
	v_pk_fma_f32 v[126:127], v[126:127], s[6:7], v[90:91] op_sel_hi:[1,0,1]
	s_waitcnt vmcnt(13)
	v_pk_fma_f32 v[128:129], v[128:129], s[6:7], v[84:85] op_sel_hi:[1,0,1]
	v_pk_fma_f32 v[130:131], v[130:131], s[6:7], v[86:87] op_sel_hi:[1,0,1]
	s_waitcnt vmcnt(12)
	v_pk_fma_f32 v[132:133], v[132:133], s[6:7], v[80:81] op_sel_hi:[1,0,1]
	v_pk_fma_f32 v[134:135], v[134:135], s[6:7], v[82:83] op_sel_hi:[1,0,1]
	s_waitcnt vmcnt(11)
	v_pk_fma_f32 v[136:137], v[136:137], s[6:7], v[76:77] op_sel_hi:[1,0,1]
	v_pk_fma_f32 v[138:139], v[138:139], s[6:7], v[78:79] op_sel_hi:[1,0,1]
	s_waitcnt vmcnt(10)
	v_pk_fma_f32 v[140:141], v[140:141], s[6:7], v[72:73] op_sel_hi:[1,0,1]
	v_pk_fma_f32 v[142:143], v[142:143], s[6:7], v[74:75] op_sel_hi:[1,0,1]
	s_waitcnt vmcnt(9)
	v_pk_fma_f32 v[144:145], v[144:145], s[6:7], v[60:61] op_sel_hi:[1,0,1]
	v_pk_fma_f32 v[146:147], v[146:147], s[6:7], v[62:63] op_sel_hi:[1,0,1]
	s_waitcnt vmcnt(8)
	v_pk_fma_f32 v[148:149], v[148:149], s[6:7], v[28:29] op_sel_hi:[1,0,1]
	v_pk_fma_f32 v[150:151], v[150:151], s[6:7], v[30:31] op_sel_hi:[1,0,1]
	s_waitcnt vmcnt(7)
	v_pk_fma_f32 v[20:21], v[20:21], s[6:7], v[64:65] op_sel_hi:[1,0,1]
	v_pk_fma_f32 v[22:23], v[22:23], s[6:7], v[66:67] op_sel_hi:[1,0,1]
	s_waitcnt vmcnt(6)
	v_pk_fma_f32 v[24:25], v[24:25], s[6:7], v[36:37] op_sel_hi:[1,0,1]
	v_pk_fma_f32 v[26:27], v[26:27], s[6:7], v[38:39] op_sel_hi:[1,0,1]
	s_waitcnt vmcnt(5)
	v_pk_fma_f32 v[40:41], v[40:41], s[6:7], v[32:33] op_sel_hi:[1,0,1]
	v_pk_fma_f32 v[42:43], v[42:43], s[6:7], v[34:35] op_sel_hi:[1,0,1]
	s_waitcnt vmcnt(4)
	v_pk_fma_f32 v[44:45], v[44:45], s[6:7], v[16:17] op_sel_hi:[1,0,1]
	v_pk_fma_f32 v[46:47], v[46:47], s[6:7], v[18:19] op_sel_hi:[1,0,1]
	s_waitcnt vmcnt(3)
	v_pk_fma_f32 v[48:49], v[48:49], s[6:7], v[12:13] op_sel_hi:[1,0,1]
	v_pk_fma_f32 v[50:51], v[50:51], s[6:7], v[14:15] op_sel_hi:[1,0,1]
	s_waitcnt vmcnt(2)
	v_pk_fma_f32 v[52:53], v[52:53], s[6:7], v[8:9] op_sel_hi:[1,0,1]
	v_pk_fma_f32 v[54:55], v[54:55], s[6:7], v[10:11] op_sel_hi:[1,0,1]
	s_waitcnt vmcnt(1)
	v_pk_fma_f32 v[56:57], v[56:57], s[6:7], v[4:5] op_sel_hi:[1,0,1]
	v_pk_fma_f32 v[58:59], v[58:59], s[6:7], v[6:7] op_sel_hi:[1,0,1]
	s_waitcnt vmcnt(0)
	v_pk_fma_f32 v[68:69], v[68:69], s[6:7], v[0:1] op_sel_hi:[1,0,1]
	v_pk_fma_f32 v[70:71], v[70:71], s[6:7], v[2:3] op_sel_hi:[1,0,1]
	global_store_dwordx4 v[160:161], v[120:123], off
	global_store_dwordx4 v[160:161], v[124:127], off offset:64
	global_store_dwordx4 v[160:161], v[128:131], off offset:128
	global_store_dwordx4 v[160:161], v[132:135], off offset:192
	global_store_dwordx4 v[162:163], v[136:139], off
	global_store_dwordx4 v[162:163], v[140:143], off offset:64
	global_store_dwordx4 v[162:163], v[144:147], off offset:128
	global_store_dwordx4 v[162:163], v[148:151], off offset:192
	global_store_dwordx4 v[164:165], v[20:23], off
	global_store_dwordx4 v[164:165], v[24:27], off offset:64
	global_store_dwordx4 v[164:165], v[40:43], off offset:128
	global_store_dwordx4 v[164:165], v[44:47], off offset:192
	global_store_dwordx4 v[166:167], v[48:51], off
	global_store_dwordx4 v[166:167], v[52:55], off offset:64
	global_store_dwordx4 v[166:167], v[56:59], off offset:128
	global_store_dwordx4 v[166:167], v[68:71], off offset:192
	s_add_i32 s7, s7, s3
	s_cmpk_lt_u32 s7, 0x100
	s_cbranch_scc1 .LBB0_798

.Lglds2_28042:
	ds_read_b128 v[152:155], v111 offset:16384
	ds_read_b128 v[156:159], v111 offset:18432
	ds_read_b128 v[160:163], v109
	ds_read_b128 v[164:167], v109 offset:2048
	ds_read_b128 v[168:171], v111 offset:20480
	ds_read_b128 v[172:175], v112 offset:16384
	ds_read_b128 v[208:211], v109 offset:4096
	ds_read_b128 v[212:215], v110
	ds_read_b128 v[216:219], v115 offset:16384
	ds_read_b128 v[220:223], v115 offset:18432
	ds_read_b128 v[224:227], v113
	ds_read_b128 v[228:231], v113 offset:2048
	ds_read_b128 v[232:235], v115 offset:20480
	ds_read_b128 v[236:239], v116 offset:16384
	ds_read_b128 v[240:243], v113 offset:4096
	ds_read_b128 v[244:247], v114
	s_setprio 1
	s_waitcnt lgkmcnt(13)
	v_mfma_i32_16x16x64_i8 v[92:95], v[152:155], v[160:163], v[92:95]
	v_mfma_i32_16x16x64_i8 v[88:91], v[156:159], v[160:163], v[88:91]
	s_waitcnt lgkmcnt(11)
	v_mfma_i32_16x16x64_i8 v[84:87], v[168:171], v[160:163], v[84:87]
	s_waitcnt lgkmcnt(10)
	v_mfma_i32_16x16x64_i8 v[80:83], v[172:175], v[160:163], v[80:83]
	v_mfma_i32_16x16x64_i8 v[60:63], v[152:155], v[164:167], v[60:63]
	v_mfma_i32_16x16x64_i8 v[40:43], v[156:159], v[164:167], v[40:43]
	v_mfma_i32_16x16x64_i8 v[36:39], v[168:171], v[164:167], v[36:39]
	v_mfma_i32_16x16x64_i8 v[28:31], v[172:175], v[164:167], v[28:31]
	s_waitcnt lgkmcnt(9)
	v_mfma_i32_16x16x64_i8 v[32:35], v[152:155], v[208:211], v[32:35]
	v_mfma_i32_16x16x64_i8 v[24:27], v[156:159], v[208:211], v[24:27]
	v_mfma_i32_16x16x64_i8 v[20:23], v[168:171], v[208:211], v[20:23]
	v_mfma_i32_16x16x64_i8 v[16:19], v[172:175], v[208:211], v[16:19]
	s_waitcnt lgkmcnt(8)
	v_mfma_i32_16x16x64_i8 v[12:15], v[152:155], v[212:215], v[12:15]
	v_mfma_i32_16x16x64_i8 v[8:11], v[156:159], v[212:215], v[8:11]
	v_mfma_i32_16x16x64_i8 v[4:7], v[168:171], v[212:215], v[4:7]
	v_mfma_i32_16x16x64_i8 v[0:3], v[172:175], v[212:215], v[0:3]
	s_setprio 0
	s_waitcnt lgkmcnt(0)
	s_barrier
	s_add_i32 s6, s15, 0x80
	s_min_u32 s6, s6, 0x1c0
	s_lshl_b32 s6, s6, 1
	s_setprio 1
	v_mfma_i32_16x16x64_i8 v[92:95], v[216:219], v[224:227], v[92:95]
	s_add_u32 m0, s16, 0x0
	v_lshl_add_u64 v[204:205], v[188:189], 0, s[6:7]
	global_load_lds_dwordx4 v[204:205], off
	v_mfma_i32_16x16x64_i8 v[88:91], v[220:223], v[224:227], v[88:91]
	v_mfma_i32_16x16x64_i8 v[84:87], v[232:235], v[224:227], v[84:87]
	s_add_u32 m0, s16, 0x1000
	v_lshl_add_u64 v[206:207], v[190:191], 0, s[6:7]
	global_load_lds_dwordx4 v[206:207], off
	v_mfma_i32_16x16x64_i8 v[80:83], v[236:239], v[224:227], v[80:83]
	v_mfma_i32_16x16x64_i8 v[60:63], v[216:219], v[228:231], v[60:63]
	s_add_u32 m0, s16, 0x2000
	v_lshl_add_u64 v[204:205], v[192:193], 0, s[6:7]
	global_load_lds_dwordx4 v[204:205], off
	v_mfma_i32_16x16x64_i8 v[40:43], v[220:223], v[228:231], v[40:43]
	v_mfma_i32_16x16x64_i8 v[36:39], v[232:235], v[228:231], v[36:39]
	s_add_u32 m0, s16, 0x3000
	v_lshl_add_u64 v[206:207], v[194:195], 0, s[6:7]
	global_load_lds_dwordx4 v[206:207], off
	v_mfma_i32_16x16x64_i8 v[28:31], v[236:239], v[228:231], v[28:31]
	v_mfma_i32_16x16x64_i8 v[32:35], v[216:219], v[240:243], v[32:35]
	s_add_u32 m0, s16, 0x4000
	v_lshl_add_u64 v[204:205], v[196:197], 0, s[6:7]
	global_load_lds_dwordx4 v[204:205], off
	v_mfma_i32_16x16x64_i8 v[24:27], v[220:223], v[240:243], v[24:27]
	v_mfma_i32_16x16x64_i8 v[20:23], v[232:235], v[240:243], v[20:23]
	s_add_u32 m0, s16, 0x5000
	v_lshl_add_u64 v[206:207], v[198:199], 0, s[6:7]
	global_load_lds_dwordx4 v[206:207], off
	v_mfma_i32_16x16x64_i8 v[16:19], v[236:239], v[240:243], v[16:19]
	v_mfma_i32_16x16x64_i8 v[12:15], v[216:219], v[244:247], v[12:15]
	s_add_u32 m0, s16, 0x6000
	v_lshl_add_u64 v[204:205], v[200:201], 0, s[6:7]
	global_load_lds_dwordx4 v[204:205], off
	v_mfma_i32_16x16x64_i8 v[8:11], v[220:223], v[244:247], v[8:11]
	v_mfma_i32_16x16x64_i8 v[4:7], v[232:235], v[244:247], v[4:7]
	s_add_u32 m0, s16, 0x7000
	v_lshl_add_u64 v[206:207], v[202:203], 0, s[6:7]
	global_load_lds_dwordx4 v[206:207], off
	v_mfma_i32_16x16x64_i8 v[0:3], v[236:239], v[244:247], v[0:3]
	s_setprio 0
	s_waitcnt vmcnt(8)
	s_barrier
	ds_read_b128 v[152:155], v111 offset:49152
	ds_read_b128 v[156:159], v111 offset:51200
	ds_read_b128 v[160:163], v109 offset:32768
	ds_read_b128 v[164:167], v109 offset:34816
	ds_read_b128 v[168:171], v111 offset:53248
	ds_read_b128 v[172:175], v112 offset:49152
	ds_read_b128 v[208:211], v109 offset:36864
	ds_read_b128 v[212:215], v110 offset:32768
	ds_read_b128 v[216:219], v115 offset:49152
	ds_read_b128 v[220:223], v115 offset:51200
	ds_read_b128 v[224:227], v113 offset:32768
	ds_read_b128 v[228:231], v113 offset:34816
	ds_read_b128 v[232:235], v115 offset:53248
	ds_read_b128 v[236:239], v116 offset:49152
	ds_read_b128 v[240:243], v113 offset:36864
	ds_read_b128 v[244:247], v114 offset:32768
	s_setprio 1
	s_waitcnt lgkmcnt(13)
	v_mfma_i32_16x16x64_i8 v[92:95], v[152:155], v[160:163], v[92:95]
	v_mfma_i32_16x16x64_i8 v[88:91], v[156:159], v[160:163], v[88:91]
	s_waitcnt lgkmcnt(11)
	v_mfma_i32_16x16x64_i8 v[84:87], v[168:171], v[160:163], v[84:87]
	s_waitcnt lgkmcnt(10)
	v_mfma_i32_16x16x64_i8 v[80:83], v[172:175], v[160:163], v[80:83]
	v_mfma_i32_16x16x64_i8 v[60:63], v[152:155], v[164:167], v[60:63]
	v_mfma_i32_16x16x64_i8 v[40:43], v[156:159], v[164:167], v[40:43]
	v_mfma_i32_16x16x64_i8 v[36:39], v[168:171], v[164:167], v[36:39]
	v_mfma_i32_16x16x64_i8 v[28:31], v[172:175], v[164:167], v[28:31]
	s_waitcnt lgkmcnt(9)
	v_mfma_i32_16x16x64_i8 v[32:35], v[152:155], v[208:211], v[32:35]
	v_mfma_i32_16x16x64_i8 v[24:27], v[156:159], v[208:211], v[24:27]
	v_mfma_i32_16x16x64_i8 v[20:23], v[168:171], v[208:211], v[20:23]
	v_mfma_i32_16x16x64_i8 v[16:19], v[172:175], v[208:211], v[16:19]
	s_waitcnt lgkmcnt(8)
	v_mfma_i32_16x16x64_i8 v[12:15], v[152:155], v[212:215], v[12:15]
	v_mfma_i32_16x16x64_i8 v[8:11], v[156:159], v[212:215], v[8:11]
	v_mfma_i32_16x16x64_i8 v[4:7], v[168:171], v[212:215], v[4:7]
	v_mfma_i32_16x16x64_i8 v[0:3], v[172:175], v[212:215], v[0:3]
	s_setprio 0
	s_waitcnt lgkmcnt(0)
	s_barrier
	s_add_i32 s6, s15, 0xc0
	s_min_u32 s6, s6, 0x1c0
	s_lshl_b32 s6, s6, 1
	s_setprio 1
	v_mfma_i32_16x16x64_i8 v[92:95], v[216:219], v[224:227], v[92:95]
	s_add_u32 m0, s16, 0x8000
	v_lshl_add_u64 v[204:205], v[188:189], 0, s[6:7]
	global_load_lds_dwordx4 v[204:205], off
	v_mfma_i32_16x16x64_i8 v[88:91], v[220:223], v[224:227], v[88:91]
	v_mfma_i32_16x16x64_i8 v[84:87], v[232:235], v[224:227], v[84:87]
	s_add_u32 m0, s16, 0x9000
	v_lshl_add_u64 v[206:207], v[190:191], 0, s[6:7]
	global_load_lds_dwordx4 v[206:207], off
	v_mfma_i32_16x16x64_i8 v[80:83], v[236:239], v[224:227], v[80:83]
	v_mfma_i32_16x16x64_i8 v[60:63], v[216:219], v[228:231], v[60:63]
	s_add_u32 m0, s16, 0xa000
	v_lshl_add_u64 v[204:205], v[192:193], 0, s[6:7]
	global_load_lds_dwordx4 v[204:205], off
	v_mfma_i32_16x16x64_i8 v[40:43], v[220:223], v[228:231], v[40:43]
	v_mfma_i32_16x16x64_i8 v[36:39], v[232:235], v[228:231], v[36:39]
	s_add_u32 m0, s16, 0xb000
	v_lshl_add_u64 v[206:207], v[194:195], 0, s[6:7]
	global_load_lds_dwordx4 v[206:207], off
	v_mfma_i32_16x16x64_i8 v[28:31], v[236:239], v[228:231], v[28:31]
	v_mfma_i32_16x16x64_i8 v[32:35], v[216:219], v[240:243], v[32:35]
	s_add_u32 m0, s16, 0xc000
	v_lshl_add_u64 v[204:205], v[196:197], 0, s[6:7]
	global_load_lds_dwordx4 v[204:205], off
	v_mfma_i32_16x16x64_i8 v[24:27], v[220:223], v[240:243], v[24:27]
	v_mfma_i32_16x16x64_i8 v[20:23], v[232:235], v[240:243], v[20:23]
	s_add_u32 m0, s16, 0xd000
	v_lshl_add_u64 v[206:207], v[198:199], 0, s[6:7]
	global_load_lds_dwordx4 v[206:207], off
	v_mfma_i32_16x16x64_i8 v[16:19], v[236:239], v[240:243], v[16:19]
	v_mfma_i32_16x16x64_i8 v[12:15], v[216:219], v[244:247], v[12:15]
	s_add_u32 m0, s16, 0xe000
	v_lshl_add_u64 v[204:205], v[200:201], 0, s[6:7]
	global_load_lds_dwordx4 v[204:205], off
	v_mfma_i32_16x16x64_i8 v[8:11], v[220:223], v[244:247], v[8:11]
	v_mfma_i32_16x16x64_i8 v[4:7], v[232:235], v[244:247], v[4:7]
	s_add_u32 m0, s16, 0xf000
	v_lshl_add_u64 v[206:207], v[202:203], 0, s[6:7]
	global_load_lds_dwordx4 v[206:207], off
	v_mfma_i32_16x16x64_i8 v[0:3], v[236:239], v[244:247], v[0:3]
	s_setprio 0
	s_waitcnt vmcnt(8)
	s_barrier
	s_add_i32 s15, s15, 0x80
	s_add_i32 s14, s14, 2
	s_cmp_lt_u32 s14, 6
	s_cbranch_scc1 .Lglds2_28042
	s_waitcnt vmcnt(0)
	v_cvt_f32_i32_e32 v92, v92
	v_cvt_f32_i32_e32 v93, v93
	v_cvt_f32_i32_e32 v94, v94
	v_cvt_f32_i32_e32 v95, v95
	v_cvt_f32_i32_e32 v88, v88
	v_cvt_f32_i32_e32 v89, v89
	v_cvt_f32_i32_e32 v90, v90
	v_cvt_f32_i32_e32 v91, v91
	v_cvt_f32_i32_e32 v84, v84
	v_cvt_f32_i32_e32 v85, v85
	v_cvt_f32_i32_e32 v86, v86
	v_cvt_f32_i32_e32 v87, v87
	v_cvt_f32_i32_e32 v80, v80
	v_cvt_f32_i32_e32 v81, v81
	v_cvt_f32_i32_e32 v82, v82
	v_cvt_f32_i32_e32 v83, v83
	v_cvt_f32_i32_e32 v60, v60
	v_cvt_f32_i32_e32 v61, v61
	v_cvt_f32_i32_e32 v62, v62
	v_cvt_f32_i32_e32 v63, v63
	v_cvt_f32_i32_e32 v40, v40
	v_cvt_f32_i32_e32 v41, v41
	v_cvt_f32_i32_e32 v42, v42
	v_cvt_f32_i32_e32 v43, v43
	v_cvt_f32_i32_e32 v36, v36
	v_cvt_f32_i32_e32 v37, v37
	v_cvt_f32_i32_e32 v38, v38
	v_cvt_f32_i32_e32 v39, v39
	v_cvt_f32_i32_e32 v28, v28
	v_cvt_f32_i32_e32 v29, v29
	v_cvt_f32_i32_e32 v30, v30
	v_cvt_f32_i32_e32 v31, v31
	v_cvt_f32_i32_e32 v32, v32
	v_cvt_f32_i32_e32 v33, v33
	v_cvt_f32_i32_e32 v34, v34
	v_cvt_f32_i32_e32 v35, v35
	v_cvt_f32_i32_e32 v24, v24
	v_cvt_f32_i32_e32 v25, v25
	v_cvt_f32_i32_e32 v26, v26
	v_cvt_f32_i32_e32 v27, v27
	v_cvt_f32_i32_e32 v20, v20
	v_cvt_f32_i32_e32 v21, v21
	v_cvt_f32_i32_e32 v22, v22
	v_cvt_f32_i32_e32 v23, v23
	v_cvt_f32_i32_e32 v16, v16
	v_cvt_f32_i32_e32 v17, v17
	v_cvt_f32_i32_e32 v18, v18
	v_cvt_f32_i32_e32 v19, v19
	v_cvt_f32_i32_e32 v12, v12
	v_cvt_f32_i32_e32 v13, v13
	v_cvt_f32_i32_e32 v14, v14
	v_cvt_f32_i32_e32 v15, v15
	v_cvt_f32_i32_e32 v8, v8
	v_cvt_f32_i32_e32 v9, v9
	v_cvt_f32_i32_e32 v10, v10
	v_cvt_f32_i32_e32 v11, v11
	v_cvt_f32_i32_e32 v4, v4
	v_cvt_f32_i32_e32 v5, v5
	v_cvt_f32_i32_e32 v6, v6
	v_cvt_f32_i32_e32 v7, v7
	v_cvt_f32_i32_e32 v0, v0
	v_cvt_f32_i32_e32 v1, v1
	v_cvt_f32_i32_e32 v2, v2
	v_cvt_f32_i32_e32 v3, v3
	s_waitcnt vmcnt(0)
	v_add_u32_e32 v96, s12, v117
	v_or_b32_e32 v146, s13, v118
	v_lshl_add_u64 v[144:145], v[96:97], 2, s[68:69]
	v_lshlrev_b32_e32 v148, 2, v146
	global_load_dword v136, v[144:145], off
	global_load_dword v138, v[144:145], off offset:64
	global_load_dword v140, v[144:145], off offset:128
	global_load_dword v142, v[144:145], off offset:192
	global_load_dwordx4 v[120:123], v148, s[0:1]
	global_load_dwordx4 v[124:127], v148, s[0:1] offset:64
	global_load_dwordx4 v[128:131], v148, s[0:1] offset:128
	global_load_dwordx4 v[132:135], v148, s[0:1] offset:192
	v_lshlrev_b32_e32 v146, 1, v146
	v_mov_b32_e32 v147, v97
	v_lshlrev_b64 v[44:45], 12, v[96:97]
	v_lshl_add_u64 v[44:45], s[64:65], 0, v[44:45]
	v_lshl_add_u64 v[44:45], v[44:45], 0, v[146:147]
	v_or_b32_e32 v52, 16, v96
	v_mov_b32_e32 v53, v97
	v_lshlrev_b64 v[46:47], 12, v[52:53]
	v_lshl_add_u64 v[46:47], s[64:65], 0, v[46:47]
	v_lshl_add_u64 v[46:47], v[46:47], 0, v[146:147]
	v_or_b32_e32 v52, 32, v96
	v_mov_b32_e32 v53, v97
	v_lshlrev_b64 v[48:49], 12, v[52:53]
	v_lshl_add_u64 v[48:49], s[64:65], 0, v[48:49]
	v_lshl_add_u64 v[48:49], v[48:49], 0, v[146:147]
	v_or_b32_e32 v52, 48, v96
	v_mov_b32_e32 v53, v97
	v_lshlrev_b64 v[50:51], 12, v[52:53]
	v_lshl_add_u64 v[50:51], s[64:65], 0, v[50:51]
	v_lshl_add_u64 v[50:51], v[50:51], 0, v[146:147]
	s_waitcnt vmcnt(0)
	v_pk_mul_f32 v[92:93], v[136:137], v[92:93] op_sel_hi:[0,1]
	v_pk_mul_f32 v[94:95], v[136:137], v[94:95] op_sel_hi:[0,1]
	v_pk_mul_f32 v[92:93], v[120:121], v[92:93]
	v_pk_mul_f32 v[94:95], v[94:95], v[122:123]
	v_cvt_pk_bf16_f32 v92, v92, v93
	v_cvt_pk_bf16_f32 v93, v94, v95
	global_store_dwordx2 v[44:45], v[92:93], off
	v_pk_mul_f32 v[88:89], v[136:137], v[88:89] op_sel_hi:[0,1]
	v_pk_mul_f32 v[90:91], v[136:137], v[90:91] op_sel_hi:[0,1]
	v_pk_mul_f32 v[88:89], v[124:125], v[88:89]
	v_pk_mul_f32 v[90:91], v[90:91], v[126:127]
	v_cvt_pk_bf16_f32 v88, v88, v89
	v_cvt_pk_bf16_f32 v89, v90, v91
	global_store_dwordx2 v[44:45], v[88:89], off offset:32
	v_pk_mul_f32 v[84:85], v[136:137], v[84:85] op_sel_hi:[0,1]
	v_pk_mul_f32 v[86:87], v[136:137], v[86:87] op_sel_hi:[0,1]
	v_pk_mul_f32 v[84:85], v[128:129], v[84:85]
	v_pk_mul_f32 v[86:87], v[86:87], v[130:131]
	v_cvt_pk_bf16_f32 v84, v84, v85
	v_cvt_pk_bf16_f32 v85, v86, v87
	global_store_dwordx2 v[44:45], v[84:85], off offset:64
	v_pk_mul_f32 v[80:81], v[136:137], v[80:81] op_sel_hi:[0,1]
	v_pk_mul_f32 v[82:83], v[136:137], v[82:83] op_sel_hi:[0,1]
	v_pk_mul_f32 v[80:81], v[132:133], v[80:81]
	v_pk_mul_f32 v[82:83], v[82:83], v[134:135]
	v_cvt_pk_bf16_f32 v80, v80, v81
	v_cvt_pk_bf16_f32 v81, v82, v83
	global_store_dwordx2 v[44:45], v[80:81], off offset:96
	v_pk_mul_f32 v[60:61], v[138:139], v[60:61] op_sel_hi:[0,1]
	v_pk_mul_f32 v[62:63], v[138:139], v[62:63] op_sel_hi:[0,1]
	v_pk_mul_f32 v[60:61], v[120:121], v[60:61]
	v_pk_mul_f32 v[62:63], v[62:63], v[122:123]
	v_cvt_pk_bf16_f32 v60, v60, v61
	v_cvt_pk_bf16_f32 v61, v62, v63
	global_store_dwordx2 v[46:47], v[60:61], off
	v_pk_mul_f32 v[40:41], v[138:139], v[40:41] op_sel_hi:[0,1]
	v_pk_mul_f32 v[42:43], v[138:139], v[42:43] op_sel_hi:[0,1]
	v_pk_mul_f32 v[40:41], v[124:125], v[40:41]
	v_pk_mul_f32 v[42:43], v[42:43], v[126:127]
	v_cvt_pk_bf16_f32 v40, v40, v41
	v_cvt_pk_bf16_f32 v41, v42, v43
	global_store_dwordx2 v[46:47], v[40:41], off offset:32
	v_pk_mul_f32 v[36:37], v[138:139], v[36:37] op_sel_hi:[0,1]
	v_pk_mul_f32 v[38:39], v[138:139], v[38:39] op_sel_hi:[0,1]
	v_pk_mul_f32 v[36:37], v[128:129], v[36:37]
	v_pk_mul_f32 v[38:39], v[38:39], v[130:131]
	v_cvt_pk_bf16_f32 v36, v36, v37
	v_cvt_pk_bf16_f32 v37, v38, v39
	global_store_dwordx2 v[46:47], v[36:37], off offset:64
	v_pk_mul_f32 v[28:29], v[138:139], v[28:29] op_sel_hi:[0,1]
	v_pk_mul_f32 v[30:31], v[138:139], v[30:31] op_sel_hi:[0,1]
	v_pk_mul_f32 v[28:29], v[132:133], v[28:29]
	v_pk_mul_f32 v[30:31], v[30:31], v[134:135]
	v_cvt_pk_bf16_f32 v28, v28, v29
	v_cvt_pk_bf16_f32 v29, v30, v31
	global_store_dwordx2 v[46:47], v[28:29], off offset:96
	v_pk_mul_f32 v[32:33], v[140:141], v[32:33] op_sel_hi:[0,1]
	v_pk_mul_f32 v[34:35], v[140:141], v[34:35] op_sel_hi:[0,1]
	v_pk_mul_f32 v[32:33], v[120:121], v[32:33]
	v_pk_mul_f32 v[34:35], v[34:35], v[122:123]
	v_cvt_pk_bf16_f32 v32, v32, v33
	v_cvt_pk_bf16_f32 v33, v34, v35
	global_store_dwordx2 v[48:49], v[32:33], off
	v_pk_mul_f32 v[24:25], v[140:141], v[24:25] op_sel_hi:[0,1]
	v_pk_mul_f32 v[26:27], v[140:141], v[26:27] op_sel_hi:[0,1]
	v_pk_mul_f32 v[24:25], v[124:125], v[24:25]
	v_pk_mul_f32 v[26:27], v[26:27], v[126:127]
	v_cvt_pk_bf16_f32 v24, v24, v25
	v_cvt_pk_bf16_f32 v25, v26, v27
	global_store_dwordx2 v[48:49], v[24:25], off offset:32
	v_pk_mul_f32 v[20:21], v[140:141], v[20:21] op_sel_hi:[0,1]
	v_pk_mul_f32 v[22:23], v[140:141], v[22:23] op_sel_hi:[0,1]
	v_pk_mul_f32 v[20:21], v[128:129], v[20:21]
	v_pk_mul_f32 v[22:23], v[22:23], v[130:131]
	v_cvt_pk_bf16_f32 v20, v20, v21
	v_cvt_pk_bf16_f32 v21, v22, v23
	global_store_dwordx2 v[48:49], v[20:21], off offset:64
	v_pk_mul_f32 v[16:17], v[140:141], v[16:17] op_sel_hi:[0,1]
	v_pk_mul_f32 v[18:19], v[140:141], v[18:19] op_sel_hi:[0,1]
	v_pk_mul_f32 v[16:17], v[132:133], v[16:17]
	v_pk_mul_f32 v[18:19], v[18:19], v[134:135]
	v_cvt_pk_bf16_f32 v16, v16, v17
	v_cvt_pk_bf16_f32 v17, v18, v19
	global_store_dwordx2 v[48:49], v[16:17], off offset:96
	v_pk_mul_f32 v[12:13], v[142:143], v[12:13] op_sel_hi:[0,1]
	v_pk_mul_f32 v[14:15], v[142:143], v[14:15] op_sel_hi:[0,1]
	v_pk_mul_f32 v[12:13], v[120:121], v[12:13]
	v_pk_mul_f32 v[14:15], v[14:15], v[122:123]
	v_cvt_pk_bf16_f32 v12, v12, v13
	v_cvt_pk_bf16_f32 v13, v14, v15
	global_store_dwordx2 v[50:51], v[12:13], off
	v_pk_mul_f32 v[8:9], v[142:143], v[8:9] op_sel_hi:[0,1]
	v_pk_mul_f32 v[10:11], v[142:143], v[10:11] op_sel_hi:[0,1]
	v_pk_mul_f32 v[8:9], v[124:125], v[8:9]
	v_pk_mul_f32 v[10:11], v[10:11], v[126:127]
	v_cvt_pk_bf16_f32 v8, v8, v9
	v_cvt_pk_bf16_f32 v9, v10, v11
	global_store_dwordx2 v[50:51], v[8:9], off offset:32
	v_pk_mul_f32 v[4:5], v[142:143], v[4:5] op_sel_hi:[0,1]
	v_pk_mul_f32 v[6:7], v[142:143], v[6:7] op_sel_hi:[0,1]
	v_pk_mul_f32 v[4:5], v[128:129], v[4:5]
	v_pk_mul_f32 v[6:7], v[6:7], v[130:131]
	v_cvt_pk_bf16_f32 v4, v4, v5
	v_cvt_pk_bf16_f32 v5, v6, v7
	global_store_dwordx2 v[50:51], v[4:5], off offset:64
	v_pk_mul_f32 v[0:1], v[142:143], v[0:1] op_sel_hi:[0,1]
	v_pk_mul_f32 v[2:3], v[142:143], v[2:3] op_sel_hi:[0,1]
	v_pk_mul_f32 v[0:1], v[132:133], v[0:1]
	v_pk_mul_f32 v[2:3], v[2:3], v[134:135]
	v_cvt_pk_bf16_f32 v0, v0, v1
	v_cvt_pk_bf16_f32 v1, v2, v3
	global_store_dwordx2 v[50:51], v[0:1], off offset:96
	s_add_i32 s8, s8, s3
	s_cmpk_lt_u32 s8, 0x200
	s_cbranch_scc1 .LBB0_889
